# GEMM K-loops: last LDS-DMA load of the six-DMA phase-2 segment moved to the start of the two-DMA phase-3 segment (phase-2 wait vmcnt 8 -> 7)
# baseline (speedup 1.0000x reference)
.LBB0_94:
	s_add_u32 s24, s22, 0x4000
	s_addc_u32 s25, s23, 0
	s_cmp_eq_u32 s60, 60
	s_cselect_b32 s28, s2, s24
	s_cselect_b32 s29, s1, s25
	s_cselect_b32 s26, s15, s48
	s_cselect_b32 s27, s13, s49
	s_add_u32 s24, s28, 0x8000
	s_addc_u32 s25, s29, 0
	s_add_i32 m0, s21, 0xc000
	s_nop 0
	global_load_lds_dwordx4 v128, s[22:23]
	s_add_i32 m0, s21, 0xe000
	s_nop 0
	global_load_lds_dwordx4 v130, s[22:23]
	ds_read_b128 v[142:145], v160
	ds_read_b128 v[146:149], v160 offset:1024
	ds_read_b128 v[168:171], v160 offset:2048
	ds_read_b128 v[172:175], v160 offset:3072
	ds_read_b128 v[176:179], v161
	ds_read_b128 v[180:183], v161 offset:1024
	ds_read_b128 v[184:187], v161 offset:2048
	ds_read_b128 v[188:191], v161 offset:3072
	ds_read_b128 v[196:199], v162
	ds_read_b128 v[200:203], v162 offset:1024
	ds_read_b128 v[204:207], v162 offset:2048
	ds_read_b128 v[208:211], v162 offset:3072
	ds_read_b128 v[212:215], v162 offset:4096
	ds_read_b128 v[216:219], v162 offset:5120
	ds_read_b128 v[220:223], v162 offset:6144
	ds_read_b128 v[224:227], v162 offset:7168
	s_waitcnt vmcnt(8)
	s_waitcnt lgkmcnt(0)
	s_barrier
	s_setprio 1
	s_waitcnt lgkmcnt(0)
	v_mfma_f32_16x16x32_bf16 v[124:127], v[142:145], v[196:199], v[124:127]
	v_mfma_f32_16x16x32_bf16 v[120:123], v[168:171], v[196:199], v[120:123]
	v_mfma_f32_16x16x32_bf16 v[108:111], v[142:145], v[204:207], v[108:111]
	v_mfma_f32_16x16x32_bf16 v[104:107], v[168:171], v[204:207], v[104:107]
	v_mfma_f32_16x16x32_bf16 v[92:95], v[142:145], v[212:215], v[92:95]
	v_mfma_f32_16x16x32_bf16 v[88:91], v[168:171], v[212:215], v[88:91]
	v_mfma_f32_16x16x32_bf16 v[76:79], v[142:145], v[220:223], v[76:79]
	v_mfma_f32_16x16x32_bf16 v[72:75], v[168:171], v[220:223], v[72:75]
	v_mfma_f32_16x16x32_bf16 v[124:127], v[146:149], v[200:203], v[124:127]
	v_mfma_f32_16x16x32_bf16 v[120:123], v[172:175], v[200:203], v[120:123]
	v_mfma_f32_16x16x32_bf16 v[108:111], v[146:149], v[208:211], v[108:111]
	v_mfma_f32_16x16x32_bf16 v[104:107], v[172:175], v[208:211], v[104:107]
	v_mfma_f32_16x16x32_bf16 v[92:95], v[146:149], v[216:219], v[92:95]
	v_mfma_f32_16x16x32_bf16 v[88:91], v[172:175], v[216:219], v[88:91]
	v_mfma_f32_16x16x32_bf16 v[76:79], v[146:149], v[224:227], v[76:79]
	v_mfma_f32_16x16x32_bf16 v[72:75], v[172:175], v[224:227], v[72:75]
	s_setprio 0
	s_setprio 1
	v_mfma_f32_16x16x32_bf16 v[116:119], v[176:179], v[196:199], v[116:119]
	v_mfma_f32_16x16x32_bf16 v[112:115], v[184:187], v[196:199], v[112:115]
	v_mfma_f32_16x16x32_bf16 v[100:103], v[176:179], v[204:207], v[100:103]
	v_mfma_f32_16x16x32_bf16 v[96:99], v[184:187], v[204:207], v[96:99]
	v_mfma_f32_16x16x32_bf16 v[84:87], v[176:179], v[212:215], v[84:87]
	v_mfma_f32_16x16x32_bf16 v[80:83], v[184:187], v[212:215], v[80:83]
	v_mfma_f32_16x16x32_bf16 v[68:71], v[176:179], v[220:223], v[68:71]
	v_mfma_f32_16x16x32_bf16 v[64:67], v[184:187], v[220:223], v[64:67]
	v_mfma_f32_16x16x32_bf16 v[116:119], v[180:183], v[200:203], v[116:119]
	v_mfma_f32_16x16x32_bf16 v[112:115], v[188:191], v[200:203], v[112:115]
	v_mfma_f32_16x16x32_bf16 v[100:103], v[180:183], v[208:211], v[100:103]
	v_mfma_f32_16x16x32_bf16 v[96:99], v[188:191], v[208:211], v[96:99]
	v_mfma_f32_16x16x32_bf16 v[84:87], v[180:183], v[216:219], v[84:87]
	v_mfma_f32_16x16x32_bf16 v[80:83], v[188:191], v[216:219], v[80:83]
	v_mfma_f32_16x16x32_bf16 v[68:71], v[180:183], v[224:227], v[68:71]
	v_mfma_f32_16x16x32_bf16 v[64:67], v[188:191], v[224:227], v[64:67]
	s_setprio 0
	s_barrier
	s_add_i32 s61, s41, s3
	s_mov_b32 m0, s61
	s_nop 0
	global_load_lds_dwordx4 v128, s[26:27]
	s_add_i32 m0, s61, 0x2000
	s_add_u32 s62, s26, 0x4000
	s_addc_u32 s63, s27, 0
	s_add_i32 s61, s42, s3
	global_load_lds_dwordx4 v130, s[26:27]
	s_mov_b32 m0, s61
	s_nop 0
	global_load_lds_dwordx4 v128, s[62:63]
	s_add_i32 m0, s61, 0x2000
	s_nop 0
	global_load_lds_dwordx4 v130, s[62:63]
	s_mov_b32 m0, s21
	s_nop 0
	global_load_lds_dwordx4 v128, s[28:29]
	ds_read_b128 v[196:199], v162 offset:16384
	ds_read_b128 v[200:203], v162 offset:17408
	ds_read_b128 v[204:207], v162 offset:18432
	ds_read_b128 v[208:211], v162 offset:19456
	ds_read_b128 v[212:215], v162 offset:20480
	ds_read_b128 v[216:219], v162 offset:21504
	ds_read_b128 v[220:223], v162 offset:22528
	ds_read_b128 v[224:227], v162 offset:23552
	s_waitcnt vmcnt(7)
	s_waitcnt lgkmcnt(0)
	s_barrier
	s_setprio 1
	s_waitcnt lgkmcnt(0)
	v_mfma_f32_16x16x32_bf16 v[60:63], v[142:145], v[196:199], v[60:63]
	v_mfma_f32_16x16x32_bf16 v[56:59], v[168:171], v[196:199], v[56:59]
	v_mfma_f32_16x16x32_bf16 v[44:47], v[142:145], v[204:207], v[44:47]
	v_mfma_f32_16x16x32_bf16 v[40:43], v[168:171], v[204:207], v[40:43]
	v_mfma_f32_16x16x32_bf16 v[28:31], v[142:145], v[212:215], v[28:31]
	v_mfma_f32_16x16x32_bf16 v[24:27], v[168:171], v[212:215], v[24:27]
	v_mfma_f32_16x16x32_bf16 v[12:15], v[142:145], v[220:223], v[12:15]
	v_mfma_f32_16x16x32_bf16 v[8:11], v[168:171], v[220:223], v[8:11]
	v_mfma_f32_16x16x32_bf16 v[60:63], v[146:149], v[200:203], v[60:63]
	v_mfma_f32_16x16x32_bf16 v[56:59], v[172:175], v[200:203], v[56:59]
	v_mfma_f32_16x16x32_bf16 v[44:47], v[146:149], v[208:211], v[44:47]
	v_mfma_f32_16x16x32_bf16 v[40:43], v[172:175], v[208:211], v[40:43]
	v_mfma_f32_16x16x32_bf16 v[28:31], v[146:149], v[216:219], v[28:31]
	v_mfma_f32_16x16x32_bf16 v[24:27], v[172:175], v[216:219], v[24:27]
	v_mfma_f32_16x16x32_bf16 v[12:15], v[146:149], v[224:227], v[12:15]
	v_mfma_f32_16x16x32_bf16 v[8:11], v[172:175], v[224:227], v[8:11]
	s_setprio 0
	s_setprio 1
	v_mfma_f32_16x16x32_bf16 v[52:55], v[176:179], v[196:199], v[52:55]
	v_mfma_f32_16x16x32_bf16 v[48:51], v[184:187], v[196:199], v[48:51]
	v_mfma_f32_16x16x32_bf16 v[36:39], v[176:179], v[204:207], v[36:39]
	v_mfma_f32_16x16x32_bf16 v[32:35], v[184:187], v[204:207], v[32:35]
	v_mfma_f32_16x16x32_bf16 v[20:23], v[176:179], v[212:215], v[20:23]
	v_mfma_f32_16x16x32_bf16 v[16:19], v[184:187], v[212:215], v[16:19]
	v_mfma_f32_16x16x32_bf16 v[4:7], v[176:179], v[220:223], v[4:7]
	v_mfma_f32_16x16x32_bf16 v[0:3], v[184:187], v[220:223], v[0:3]
	v_mfma_f32_16x16x32_bf16 v[52:55], v[180:183], v[200:203], v[52:55]
	v_mfma_f32_16x16x32_bf16 v[48:51], v[188:191], v[200:203], v[48:51]
	v_mfma_f32_16x16x32_bf16 v[36:39], v[180:183], v[208:211], v[36:39]
	v_mfma_f32_16x16x32_bf16 v[32:35], v[188:191], v[208:211], v[32:35]
	v_mfma_f32_16x16x32_bf16 v[20:23], v[180:183], v[216:219], v[20:23]
	v_mfma_f32_16x16x32_bf16 v[16:19], v[188:191], v[216:219], v[16:19]
	v_mfma_f32_16x16x32_bf16 v[4:7], v[180:183], v[224:227], v[4:7]
	v_mfma_f32_16x16x32_bf16 v[0:3], v[188:191], v[224:227], v[0:3]
	s_setprio 0
	s_barrier
	s_mov_b32 m0, s30
	s_nop 0
	global_load_lds_dwordx4 v130, s[28:29]
	s_add_i32 s61, 0, 0x18000
	v_add_u32_e32 v132, s61, v135
	s_add_i32 s62, 0, 0x1c000
	s_add_u32 s28, s28, 0x4000
	s_addc_u32 s29, s29, 0
	s_mov_b32 m0, s31
	s_nop 0
	global_load_lds_dwordx4 v128, s[28:29]
	s_mov_b32 m0, s33
	s_nop 0
	global_load_lds_dwordx4 v130, s[28:29]
	ds_read_b128 v[142:145], v132
	ds_read_b128 v[146:149], v132 offset:1024
	ds_read_b128 v[168:171], v132 offset:2048
	ds_read_b128 v[172:175], v132 offset:3072
	v_add_u32_e32 v132, s62, v135
	ds_read_b128 v[176:179], v132
	ds_read_b128 v[180:183], v132 offset:1024
	ds_read_b128 v[184:187], v132 offset:2048
	ds_read_b128 v[188:191], v132 offset:3072
	ds_read_b128 v[196:199], v162 offset:32768
	ds_read_b128 v[200:203], v162 offset:33792
	ds_read_b128 v[204:207], v162 offset:34816
	ds_read_b128 v[208:211], v162 offset:35840
	ds_read_b128 v[212:215], v162 offset:36864
	ds_read_b128 v[216:219], v162 offset:37888
	ds_read_b128 v[220:223], v162 offset:38912
	ds_read_b128 v[224:227], v162 offset:39936
	s_waitcnt vmcnt(8)
	s_waitcnt lgkmcnt(0)
	s_barrier
	s_setprio 1
	s_waitcnt lgkmcnt(0)
	v_mfma_f32_16x16x32_bf16 v[124:127], v[142:145], v[196:199], v[124:127]
	v_mfma_f32_16x16x32_bf16 v[120:123], v[168:171], v[196:199], v[120:123]
	v_mfma_f32_16x16x32_bf16 v[108:111], v[142:145], v[204:207], v[108:111]
	v_mfma_f32_16x16x32_bf16 v[104:107], v[168:171], v[204:207], v[104:107]
	v_mfma_f32_16x16x32_bf16 v[92:95], v[142:145], v[212:215], v[92:95]
	v_mfma_f32_16x16x32_bf16 v[88:91], v[168:171], v[212:215], v[88:91]
	v_mfma_f32_16x16x32_bf16 v[76:79], v[142:145], v[220:223], v[76:79]
	v_mfma_f32_16x16x32_bf16 v[72:75], v[168:171], v[220:223], v[72:75]
	v_mfma_f32_16x16x32_bf16 v[124:127], v[146:149], v[200:203], v[124:127]
	v_mfma_f32_16x16x32_bf16 v[120:123], v[172:175], v[200:203], v[120:123]
	v_mfma_f32_16x16x32_bf16 v[108:111], v[146:149], v[208:211], v[108:111]
	v_mfma_f32_16x16x32_bf16 v[104:107], v[172:175], v[208:211], v[104:107]
	v_mfma_f32_16x16x32_bf16 v[92:95], v[146:149], v[216:219], v[92:95]
	v_mfma_f32_16x16x32_bf16 v[88:91], v[172:175], v[216:219], v[88:91]
	v_mfma_f32_16x16x32_bf16 v[76:79], v[146:149], v[224:227], v[76:79]
	v_mfma_f32_16x16x32_bf16 v[72:75], v[172:175], v[224:227], v[72:75]
	s_setprio 0
	s_setprio 1
	v_mfma_f32_16x16x32_bf16 v[116:119], v[176:179], v[196:199], v[116:119]
	v_mfma_f32_16x16x32_bf16 v[112:115], v[184:187], v[196:199], v[112:115]
	v_mfma_f32_16x16x32_bf16 v[100:103], v[176:179], v[204:207], v[100:103]
	v_mfma_f32_16x16x32_bf16 v[96:99], v[184:187], v[204:207], v[96:99]
	v_mfma_f32_16x16x32_bf16 v[84:87], v[176:179], v[212:215], v[84:87]
	v_mfma_f32_16x16x32_bf16 v[80:83], v[184:187], v[212:215], v[80:83]
	v_mfma_f32_16x16x32_bf16 v[68:71], v[176:179], v[220:223], v[68:71]
	v_mfma_f32_16x16x32_bf16 v[64:67], v[184:187], v[220:223], v[64:67]
	v_mfma_f32_16x16x32_bf16 v[116:119], v[180:183], v[200:203], v[116:119]
	v_mfma_f32_16x16x32_bf16 v[112:115], v[188:191], v[200:203], v[112:115]
	v_mfma_f32_16x16x32_bf16 v[100:103], v[180:183], v[208:211], v[100:103]
	v_mfma_f32_16x16x32_bf16 v[96:99], v[188:191], v[208:211], v[96:99]
	v_mfma_f32_16x16x32_bf16 v[84:87], v[180:183], v[216:219], v[84:87]
	v_mfma_f32_16x16x32_bf16 v[80:83], v[188:191], v[216:219], v[80:83]
	v_mfma_f32_16x16x32_bf16 v[68:71], v[180:183], v[224:227], v[68:71]
	v_mfma_f32_16x16x32_bf16 v[64:67], v[188:191], v[224:227], v[64:67]
	s_setprio 0
	s_barrier
	s_add_u32 s28, s26, 0x8000
	s_addc_u32 s29, s27, 0
	s_add_i32 s61, s61, s3
	s_mov_b32 m0, s61
	s_nop 0
	global_load_lds_dwordx4 v128, s[28:29]
	s_add_i32 m0, s61, 0x2000
	s_add_u32 s26, s26, 0xc000
	s_addc_u32 s27, s27, 0
	global_load_lds_dwordx4 v130, s[28:29]
	s_add_i32 s28, s62, s3
	s_mov_b32 m0, s28
	s_nop 0
	global_load_lds_dwordx4 v128, s[26:27]
	s_add_i32 m0, s28, 0x2000
	s_nop 0
	global_load_lds_dwordx4 v130, s[26:27]
	s_mov_b32 m0, s37
	s_nop 0
	global_load_lds_dwordx4 v128, s[24:25]
	s_mov_b32 m0, s38
	s_nop 0
	global_load_lds_dwordx4 v130, s[24:25]
	ds_read_b128 v[196:199], v162 offset:49152
	ds_read_b128 v[200:203], v162 offset:50176
	ds_read_b128 v[204:207], v162 offset:51200
	ds_read_b128 v[208:211], v162 offset:52224
	ds_read_b128 v[212:215], v162 offset:53248
	ds_read_b128 v[216:219], v162 offset:54272
	ds_read_b128 v[220:223], v162 offset:55296
	ds_read_b128 v[224:227], v162 offset:56320
	s_waitcnt vmcnt(8)
	s_waitcnt lgkmcnt(0)
	s_barrier
	s_setprio 1
	s_waitcnt lgkmcnt(0)
	v_mfma_f32_16x16x32_bf16 v[60:63], v[142:145], v[196:199], v[60:63]
	v_mfma_f32_16x16x32_bf16 v[56:59], v[168:171], v[196:199], v[56:59]
	v_mfma_f32_16x16x32_bf16 v[44:47], v[142:145], v[204:207], v[44:47]
	v_mfma_f32_16x16x32_bf16 v[40:43], v[168:171], v[204:207], v[40:43]
	v_mfma_f32_16x16x32_bf16 v[28:31], v[142:145], v[212:215], v[28:31]
	v_mfma_f32_16x16x32_bf16 v[24:27], v[168:171], v[212:215], v[24:27]
	v_mfma_f32_16x16x32_bf16 v[12:15], v[142:145], v[220:223], v[12:15]
	v_mfma_f32_16x16x32_bf16 v[8:11], v[168:171], v[220:223], v[8:11]
	v_mfma_f32_16x16x32_bf16 v[60:63], v[146:149], v[200:203], v[60:63]
	v_mfma_f32_16x16x32_bf16 v[56:59], v[172:175], v[200:203], v[56:59]
	v_mfma_f32_16x16x32_bf16 v[44:47], v[146:149], v[208:211], v[44:47]
	v_mfma_f32_16x16x32_bf16 v[40:43], v[172:175], v[208:211], v[40:43]
	v_mfma_f32_16x16x32_bf16 v[28:31], v[146:149], v[216:219], v[28:31]
	v_mfma_f32_16x16x32_bf16 v[24:27], v[172:175], v[216:219], v[24:27]
	v_mfma_f32_16x16x32_bf16 v[12:15], v[146:149], v[224:227], v[12:15]
	v_mfma_f32_16x16x32_bf16 v[8:11], v[172:175], v[224:227], v[8:11]
	s_setprio 0
	s_setprio 1
	v_mfma_f32_16x16x32_bf16 v[52:55], v[176:179], v[196:199], v[52:55]
	v_mfma_f32_16x16x32_bf16 v[48:51], v[184:187], v[196:199], v[48:51]
	v_mfma_f32_16x16x32_bf16 v[36:39], v[176:179], v[204:207], v[36:39]
	v_mfma_f32_16x16x32_bf16 v[32:35], v[184:187], v[204:207], v[32:35]
	v_mfma_f32_16x16x32_bf16 v[20:23], v[176:179], v[212:215], v[20:23]
	v_mfma_f32_16x16x32_bf16 v[16:19], v[184:187], v[212:215], v[16:19]
	v_mfma_f32_16x16x32_bf16 v[4:7], v[176:179], v[220:223], v[4:7]
	v_mfma_f32_16x16x32_bf16 v[0:3], v[184:187], v[220:223], v[0:3]
	v_mfma_f32_16x16x32_bf16 v[52:55], v[180:183], v[200:203], v[52:55]
	v_mfma_f32_16x16x32_bf16 v[48:51], v[188:191], v[200:203], v[48:51]
	v_mfma_f32_16x16x32_bf16 v[36:39], v[180:183], v[208:211], v[36:39]
	v_mfma_f32_16x16x32_bf16 v[32:35], v[188:191], v[208:211], v[32:35]
	v_mfma_f32_16x16x32_bf16 v[20:23], v[180:183], v[216:219], v[20:23]
	v_mfma_f32_16x16x32_bf16 v[16:19], v[188:191], v[216:219], v[16:19]
	v_mfma_f32_16x16x32_bf16 v[4:7], v[180:183], v[224:227], v[4:7]
	v_mfma_f32_16x16x32_bf16 v[0:3], v[188:191], v[224:227], v[0:3]
	s_setprio 0
	s_barrier
	s_add_i32 s60, s60, 2
	s_add_u32 s22, s22, 0x10000
	s_addc_u32 s23, s23, 0
	s_add_u32 s48, s48, 0x10000
	s_addc_u32 s49, s49, 0
	s_cmp_gt_u32 s60, 61
	s_cbranch_scc0 .LBB0_94
	s_and_b64 vcc, exec, s[10:11]
	s_cbranch_vccz .LBB0_97
	s_barrier

.LBB0_373:
	s_add_u32 s30, s28, 0x4000
	s_addc_u32 s31, s29, 0
	s_cmp_eq_u32 s49, 60
	s_cselect_b32 s36, s13, s30
	s_cselect_b32 s37, s2, s31
	s_cselect_b32 s34, s21, s27
	s_cselect_b32 s35, s19, s48
	s_add_u32 s30, s36, 0x8000
	s_addc_u32 s31, s37, 0
	s_add_i32 m0, s33, 0xc000
	s_nop 0
	global_load_lds_dwordx4 v144, s[28:29]
	s_add_i32 m0, s33, 0xe000
	s_nop 0
	global_load_lds_dwordx4 v146, s[28:29]
	ds_read_b128 v[128:131], v164
	ds_read_b128 v[132:135], v164 offset:1024
	ds_read_b128 v[136:139], v164 offset:2048
	ds_read_b128 v[140:143], v164 offset:3072
	ds_read_b128 v[154:157], v166
	ds_read_b128 v[170:173], v166 offset:1024
	ds_read_b128 v[174:177], v166 offset:2048
	ds_read_b128 v[178:181], v166 offset:3072
	ds_read_b128 v[182:185], v168
	ds_read_b128 v[186:189], v168 offset:1024
	ds_read_b128 v[190:193], v168 offset:2048
	ds_read_b128 v[196:199], v168 offset:3072
	ds_read_b128 v[200:203], v168 offset:4096
	ds_read_b128 v[204:207], v168 offset:5120
	ds_read_b128 v[208:211], v168 offset:6144
	ds_read_b128 v[212:215], v168 offset:7168
	s_waitcnt vmcnt(8)
	s_waitcnt lgkmcnt(0)
	s_barrier
	s_setprio 1
	s_waitcnt lgkmcnt(0)
	v_mfma_f32_16x16x32_bf16 v[124:127], v[128:131], v[182:185], v[124:127]
	v_mfma_f32_16x16x32_bf16 v[120:123], v[136:139], v[182:185], v[120:123]
	v_mfma_f32_16x16x32_bf16 v[108:111], v[128:131], v[190:193], v[108:111]
	v_mfma_f32_16x16x32_bf16 v[104:107], v[136:139], v[190:193], v[104:107]
	v_mfma_f32_16x16x32_bf16 v[92:95], v[128:131], v[200:203], v[92:95]
	v_mfma_f32_16x16x32_bf16 v[88:91], v[136:139], v[200:203], v[88:91]
	v_mfma_f32_16x16x32_bf16 v[76:79], v[128:131], v[208:211], v[76:79]
	v_mfma_f32_16x16x32_bf16 v[72:75], v[136:139], v[208:211], v[72:75]
	v_mfma_f32_16x16x32_bf16 v[124:127], v[132:135], v[186:189], v[124:127]
	v_mfma_f32_16x16x32_bf16 v[120:123], v[140:143], v[186:189], v[120:123]
	v_mfma_f32_16x16x32_bf16 v[108:111], v[132:135], v[196:199], v[108:111]
	v_mfma_f32_16x16x32_bf16 v[104:107], v[140:143], v[196:199], v[104:107]
	v_mfma_f32_16x16x32_bf16 v[92:95], v[132:135], v[204:207], v[92:95]
	v_mfma_f32_16x16x32_bf16 v[88:91], v[140:143], v[204:207], v[88:91]
	v_mfma_f32_16x16x32_bf16 v[76:79], v[132:135], v[212:215], v[76:79]
	v_mfma_f32_16x16x32_bf16 v[72:75], v[140:143], v[212:215], v[72:75]
	s_setprio 0
	s_setprio 1
	v_mfma_f32_16x16x32_bf16 v[116:119], v[154:157], v[182:185], v[116:119]
	v_mfma_f32_16x16x32_bf16 v[112:115], v[174:177], v[182:185], v[112:115]
	v_mfma_f32_16x16x32_bf16 v[100:103], v[154:157], v[190:193], v[100:103]
	v_mfma_f32_16x16x32_bf16 v[96:99], v[174:177], v[190:193], v[96:99]
	v_mfma_f32_16x16x32_bf16 v[84:87], v[154:157], v[200:203], v[84:87]
	v_mfma_f32_16x16x32_bf16 v[80:83], v[174:177], v[200:203], v[80:83]
	v_mfma_f32_16x16x32_bf16 v[68:71], v[154:157], v[208:211], v[68:71]
	v_mfma_f32_16x16x32_bf16 v[64:67], v[174:177], v[208:211], v[64:67]
	v_mfma_f32_16x16x32_bf16 v[116:119], v[170:173], v[186:189], v[116:119]
	v_mfma_f32_16x16x32_bf16 v[112:115], v[178:181], v[186:189], v[112:115]
	v_mfma_f32_16x16x32_bf16 v[100:103], v[170:173], v[196:199], v[100:103]
	v_mfma_f32_16x16x32_bf16 v[96:99], v[178:181], v[196:199], v[96:99]
	v_mfma_f32_16x16x32_bf16 v[84:87], v[170:173], v[204:207], v[84:87]
	v_mfma_f32_16x16x32_bf16 v[80:83], v[178:181], v[204:207], v[80:83]
	v_mfma_f32_16x16x32_bf16 v[68:71], v[170:173], v[212:215], v[68:71]
	v_mfma_f32_16x16x32_bf16 v[64:67], v[178:181], v[212:215], v[64:67]
	s_setprio 0
	s_barrier
	s_add_i32 s61, s57, s3
	s_mov_b32 m0, s61
	s_nop 0
	global_load_lds_dwordx4 v144, s[34:35]
	s_add_i32 m0, s61, 0x2000
	s_add_u32 s62, s34, 0x4000
	s_addc_u32 s63, s35, 0
	s_add_i32 s61, s60, s3
	global_load_lds_dwordx4 v146, s[34:35]
	s_mov_b32 m0, s61
	s_nop 0
	global_load_lds_dwordx4 v144, s[62:63]
	s_add_i32 m0, s61, 0x2000
	s_nop 0
	global_load_lds_dwordx4 v146, s[62:63]
	s_mov_b32 m0, s33
	s_nop 0
	global_load_lds_dwordx4 v144, s[36:37]
	ds_read_b128 v[182:185], v168 offset:16384
	ds_read_b128 v[186:189], v168 offset:17408
	ds_read_b128 v[190:193], v168 offset:18432
	ds_read_b128 v[196:199], v168 offset:19456
	ds_read_b128 v[200:203], v168 offset:20480
	ds_read_b128 v[204:207], v168 offset:21504
	ds_read_b128 v[208:211], v168 offset:22528
	ds_read_b128 v[212:215], v168 offset:23552
	s_waitcnt vmcnt(7)
	s_waitcnt lgkmcnt(0)
	s_barrier
	s_setprio 1
	s_waitcnt lgkmcnt(0)
	v_mfma_f32_16x16x32_bf16 v[60:63], v[128:131], v[182:185], v[60:63]
	v_mfma_f32_16x16x32_bf16 v[56:59], v[136:139], v[182:185], v[56:59]
	v_mfma_f32_16x16x32_bf16 v[44:47], v[128:131], v[190:193], v[44:47]
	v_mfma_f32_16x16x32_bf16 v[40:43], v[136:139], v[190:193], v[40:43]
	v_mfma_f32_16x16x32_bf16 v[28:31], v[128:131], v[200:203], v[28:31]
	v_mfma_f32_16x16x32_bf16 v[24:27], v[136:139], v[200:203], v[24:27]
	v_mfma_f32_16x16x32_bf16 v[12:15], v[128:131], v[208:211], v[12:15]
	v_mfma_f32_16x16x32_bf16 v[8:11], v[136:139], v[208:211], v[8:11]
	v_mfma_f32_16x16x32_bf16 v[60:63], v[132:135], v[186:189], v[60:63]
	v_mfma_f32_16x16x32_bf16 v[56:59], v[140:143], v[186:189], v[56:59]
	v_mfma_f32_16x16x32_bf16 v[44:47], v[132:135], v[196:199], v[44:47]
	v_mfma_f32_16x16x32_bf16 v[40:43], v[140:143], v[196:199], v[40:43]
	v_mfma_f32_16x16x32_bf16 v[28:31], v[132:135], v[204:207], v[28:31]
	v_mfma_f32_16x16x32_bf16 v[24:27], v[140:143], v[204:207], v[24:27]
	v_mfma_f32_16x16x32_bf16 v[12:15], v[132:135], v[212:215], v[12:15]
	v_mfma_f32_16x16x32_bf16 v[8:11], v[140:143], v[212:215], v[8:11]
	s_setprio 0
	s_setprio 1
	v_mfma_f32_16x16x32_bf16 v[52:55], v[154:157], v[182:185], v[52:55]
	v_mfma_f32_16x16x32_bf16 v[48:51], v[174:177], v[182:185], v[48:51]
	v_mfma_f32_16x16x32_bf16 v[36:39], v[154:157], v[190:193], v[36:39]
	v_mfma_f32_16x16x32_bf16 v[32:35], v[174:177], v[190:193], v[32:35]
	v_mfma_f32_16x16x32_bf16 v[20:23], v[154:157], v[200:203], v[20:23]
	v_mfma_f32_16x16x32_bf16 v[16:19], v[174:177], v[200:203], v[16:19]
	v_mfma_f32_16x16x32_bf16 v[4:7], v[154:157], v[208:211], v[4:7]
	v_mfma_f32_16x16x32_bf16 v[0:3], v[174:177], v[208:211], v[0:3]
	v_mfma_f32_16x16x32_bf16 v[52:55], v[170:173], v[186:189], v[52:55]
	v_mfma_f32_16x16x32_bf16 v[48:51], v[178:181], v[186:189], v[48:51]
	v_mfma_f32_16x16x32_bf16 v[36:39], v[170:173], v[196:199], v[36:39]
	v_mfma_f32_16x16x32_bf16 v[32:35], v[178:181], v[196:199], v[32:35]
	v_mfma_f32_16x16x32_bf16 v[20:23], v[170:173], v[204:207], v[20:23]
	v_mfma_f32_16x16x32_bf16 v[16:19], v[178:181], v[204:207], v[16:19]
	v_mfma_f32_16x16x32_bf16 v[4:7], v[170:173], v[212:215], v[4:7]
	v_mfma_f32_16x16x32_bf16 v[0:3], v[178:181], v[212:215], v[0:3]
	s_setprio 0
	s_barrier
	s_mov_b32 m0, s38
	s_nop 0
	global_load_lds_dwordx4 v146, s[36:37]
	s_add_i32 s61, 0, 0x18000
	s_add_i32 s62, 0, 0x1c000
	v_add_u32_e32 v140, s61, v162
	v_add_u32_e32 v148, s62, v162
	s_add_u32 s36, s36, 0x4000
	s_addc_u32 s37, s37, 0
	s_mov_b32 m0, s39
	s_nop 0
	global_load_lds_dwordx4 v144, s[36:37]
	s_mov_b32 m0, s40
	s_nop 0
	global_load_lds_dwordx4 v146, s[36:37]
	ds_read_b128 v[128:131], v140
	ds_read_b128 v[132:135], v140 offset:1024
	ds_read_b128 v[136:139], v140 offset:2048
	ds_read_b128 v[140:143], v140 offset:3072
	ds_read_b128 v[154:157], v148
	ds_read_b128 v[170:173], v148 offset:1024
	ds_read_b128 v[174:177], v148 offset:2048
	ds_read_b128 v[178:181], v148 offset:3072
	ds_read_b128 v[182:185], v168 offset:32768
	ds_read_b128 v[186:189], v168 offset:33792
	ds_read_b128 v[190:193], v168 offset:34816
	ds_read_b128 v[196:199], v168 offset:35840
	ds_read_b128 v[200:203], v168 offset:36864
	ds_read_b128 v[204:207], v168 offset:37888
	ds_read_b128 v[208:211], v168 offset:38912
	ds_read_b128 v[212:215], v168 offset:39936
	s_waitcnt vmcnt(8)
	s_waitcnt lgkmcnt(0)
	s_barrier
	s_setprio 1
	s_waitcnt lgkmcnt(0)
	v_mfma_f32_16x16x32_bf16 v[124:127], v[128:131], v[182:185], v[124:127]
	v_mfma_f32_16x16x32_bf16 v[120:123], v[136:139], v[182:185], v[120:123]
	v_mfma_f32_16x16x32_bf16 v[108:111], v[128:131], v[190:193], v[108:111]
	v_mfma_f32_16x16x32_bf16 v[104:107], v[136:139], v[190:193], v[104:107]
	v_mfma_f32_16x16x32_bf16 v[92:95], v[128:131], v[200:203], v[92:95]
	v_mfma_f32_16x16x32_bf16 v[88:91], v[136:139], v[200:203], v[88:91]
	v_mfma_f32_16x16x32_bf16 v[76:79], v[128:131], v[208:211], v[76:79]
	v_mfma_f32_16x16x32_bf16 v[72:75], v[136:139], v[208:211], v[72:75]
	v_mfma_f32_16x16x32_bf16 v[124:127], v[132:135], v[186:189], v[124:127]
	v_mfma_f32_16x16x32_bf16 v[120:123], v[140:143], v[186:189], v[120:123]
	v_mfma_f32_16x16x32_bf16 v[108:111], v[132:135], v[196:199], v[108:111]
	v_mfma_f32_16x16x32_bf16 v[104:107], v[140:143], v[196:199], v[104:107]
	v_mfma_f32_16x16x32_bf16 v[92:95], v[132:135], v[204:207], v[92:95]
	v_mfma_f32_16x16x32_bf16 v[88:91], v[140:143], v[204:207], v[88:91]
	v_mfma_f32_16x16x32_bf16 v[76:79], v[132:135], v[212:215], v[76:79]
	v_mfma_f32_16x16x32_bf16 v[72:75], v[140:143], v[212:215], v[72:75]
	s_setprio 0
	s_setprio 1
	v_mfma_f32_16x16x32_bf16 v[116:119], v[154:157], v[182:185], v[116:119]
	v_mfma_f32_16x16x32_bf16 v[112:115], v[174:177], v[182:185], v[112:115]
	v_mfma_f32_16x16x32_bf16 v[100:103], v[154:157], v[190:193], v[100:103]
	v_mfma_f32_16x16x32_bf16 v[96:99], v[174:177], v[190:193], v[96:99]
	v_mfma_f32_16x16x32_bf16 v[84:87], v[154:157], v[200:203], v[84:87]
	v_mfma_f32_16x16x32_bf16 v[80:83], v[174:177], v[200:203], v[80:83]
	v_mfma_f32_16x16x32_bf16 v[68:71], v[154:157], v[208:211], v[68:71]
	v_mfma_f32_16x16x32_bf16 v[64:67], v[174:177], v[208:211], v[64:67]
	v_mfma_f32_16x16x32_bf16 v[116:119], v[170:173], v[186:189], v[116:119]
	v_mfma_f32_16x16x32_bf16 v[112:115], v[178:181], v[186:189], v[112:115]
	v_mfma_f32_16x16x32_bf16 v[100:103], v[170:173], v[196:199], v[100:103]
	v_mfma_f32_16x16x32_bf16 v[96:99], v[178:181], v[196:199], v[96:99]
	v_mfma_f32_16x16x32_bf16 v[84:87], v[170:173], v[204:207], v[84:87]
	v_mfma_f32_16x16x32_bf16 v[80:83], v[178:181], v[204:207], v[80:83]
	v_mfma_f32_16x16x32_bf16 v[68:71], v[170:173], v[212:215], v[68:71]
	v_mfma_f32_16x16x32_bf16 v[64:67], v[178:181], v[212:215], v[64:67]
	s_setprio 0
	s_barrier
	s_add_u32 s36, s34, 0x8000
	s_addc_u32 s37, s35, 0
	s_add_i32 s61, s61, s3
	s_mov_b32 m0, s61
	s_nop 0
	global_load_lds_dwordx4 v144, s[36:37]
	s_add_i32 m0, s61, 0x2000
	s_add_u32 s34, s34, 0xc000
	s_addc_u32 s35, s35, 0
	global_load_lds_dwordx4 v146, s[36:37]
	s_add_i32 s36, s62, s3
	s_mov_b32 m0, s36
	s_nop 0
	global_load_lds_dwordx4 v144, s[34:35]
	s_add_i32 m0, s36, 0x2000
	s_nop 0
	global_load_lds_dwordx4 v146, s[34:35]
	s_mov_b32 m0, s46
	s_nop 0
	global_load_lds_dwordx4 v144, s[30:31]
	s_mov_b32 m0, s47
	s_nop 0
	global_load_lds_dwordx4 v146, s[30:31]
	ds_read_b128 v[182:185], v168 offset:49152
	ds_read_b128 v[186:189], v168 offset:50176
	ds_read_b128 v[190:193], v168 offset:51200
	ds_read_b128 v[196:199], v168 offset:52224
	ds_read_b128 v[200:203], v168 offset:53248
	ds_read_b128 v[204:207], v168 offset:54272
	ds_read_b128 v[208:211], v168 offset:55296
	ds_read_b128 v[212:215], v168 offset:56320
	s_waitcnt vmcnt(8)
	s_waitcnt lgkmcnt(0)
	s_barrier
	s_setprio 1
	s_waitcnt lgkmcnt(0)
	v_mfma_f32_16x16x32_bf16 v[60:63], v[128:131], v[182:185], v[60:63]
	v_mfma_f32_16x16x32_bf16 v[56:59], v[136:139], v[182:185], v[56:59]
	v_mfma_f32_16x16x32_bf16 v[44:47], v[128:131], v[190:193], v[44:47]
	v_mfma_f32_16x16x32_bf16 v[40:43], v[136:139], v[190:193], v[40:43]
	v_mfma_f32_16x16x32_bf16 v[28:31], v[128:131], v[200:203], v[28:31]
	v_mfma_f32_16x16x32_bf16 v[24:27], v[136:139], v[200:203], v[24:27]
	v_mfma_f32_16x16x32_bf16 v[12:15], v[128:131], v[208:211], v[12:15]
	v_mfma_f32_16x16x32_bf16 v[8:11], v[136:139], v[208:211], v[8:11]
	v_mfma_f32_16x16x32_bf16 v[60:63], v[132:135], v[186:189], v[60:63]
	v_mfma_f32_16x16x32_bf16 v[56:59], v[140:143], v[186:189], v[56:59]
	v_mfma_f32_16x16x32_bf16 v[44:47], v[132:135], v[196:199], v[44:47]
	v_mfma_f32_16x16x32_bf16 v[40:43], v[140:143], v[196:199], v[40:43]
	v_mfma_f32_16x16x32_bf16 v[28:31], v[132:135], v[204:207], v[28:31]
	v_mfma_f32_16x16x32_bf16 v[24:27], v[140:143], v[204:207], v[24:27]
	v_mfma_f32_16x16x32_bf16 v[12:15], v[132:135], v[212:215], v[12:15]
	v_mfma_f32_16x16x32_bf16 v[8:11], v[140:143], v[212:215], v[8:11]
	s_setprio 0
	s_setprio 1
	v_mfma_f32_16x16x32_bf16 v[52:55], v[154:157], v[182:185], v[52:55]
	v_mfma_f32_16x16x32_bf16 v[48:51], v[174:177], v[182:185], v[48:51]
	v_mfma_f32_16x16x32_bf16 v[36:39], v[154:157], v[190:193], v[36:39]
	v_mfma_f32_16x16x32_bf16 v[32:35], v[174:177], v[190:193], v[32:35]
	v_mfma_f32_16x16x32_bf16 v[20:23], v[154:157], v[200:203], v[20:23]
	v_mfma_f32_16x16x32_bf16 v[16:19], v[174:177], v[200:203], v[16:19]
	v_mfma_f32_16x16x32_bf16 v[4:7], v[154:157], v[208:211], v[4:7]
	v_mfma_f32_16x16x32_bf16 v[0:3], v[174:177], v[208:211], v[0:3]
	v_mfma_f32_16x16x32_bf16 v[52:55], v[170:173], v[186:189], v[52:55]
	v_mfma_f32_16x16x32_bf16 v[48:51], v[178:181], v[186:189], v[48:51]
	v_mfma_f32_16x16x32_bf16 v[36:39], v[170:173], v[196:199], v[36:39]
	v_mfma_f32_16x16x32_bf16 v[32:35], v[178:181], v[196:199], v[32:35]
	v_mfma_f32_16x16x32_bf16 v[20:23], v[170:173], v[204:207], v[20:23]
	v_mfma_f32_16x16x32_bf16 v[16:19], v[178:181], v[204:207], v[16:19]
	v_mfma_f32_16x16x32_bf16 v[4:7], v[170:173], v[212:215], v[4:7]
	v_mfma_f32_16x16x32_bf16 v[0:3], v[178:181], v[212:215], v[0:3]
	s_setprio 0
	s_barrier
	s_add_i32 s49, s49, 2
	s_add_u32 s28, s28, 0x10000
	s_addc_u32 s29, s29, 0
	s_add_u32 s27, s27, 0x10000
	s_addc_u32 s48, s48, 0
	s_cmp_gt_u32 s49, 61
	s_cbranch_scc0 .LBB0_373
	s_and_b64 vcc, exec, s[16:17]
	s_cbranch_vccz .LBB0_376
	s_barrier

.LBB0_469:
	s_add_u32 s28, s26, 0x4000
	s_addc_u32 s29, s27, 0
	s_cmp_eq_u32 s49, 60
	s_cselect_b32 s34, s2, s28
	s_cselect_b32 s35, s1, s29
	s_cselect_b32 s30, s19, s25
	s_cselect_b32 s31, s17, s48
	s_add_u32 s28, s34, 0x8000
	s_addc_u32 s29, s35, 0
	s_add_i32 m0, s33, 0xc000
	s_nop 0
	global_load_lds_dwordx4 v176, s[26:27]
	s_add_i32 m0, s33, 0xe000
	s_nop 0
	global_load_lds_dwordx4 v178, s[26:27]
	ds_read_b128 v[128:131], v197
	ds_read_b128 v[132:135], v197 offset:1024
	ds_read_b128 v[136:139], v197 offset:2048
	ds_read_b128 v[140:143], v197 offset:3072
	ds_read_b128 v[144:147], v198
	ds_read_b128 v[148:151], v198 offset:1024
	ds_read_b128 v[152:155], v198 offset:2048
	ds_read_b128 v[156:159], v198 offset:3072
	ds_read_b128 v[160:163], v199
	ds_read_b128 v[164:167], v199 offset:1024
	ds_read_b128 v[168:171], v199 offset:2048
	ds_read_b128 v[172:175], v199 offset:3072
	ds_read_b128 v[188:191], v199 offset:4096
	ds_read_b128 v[202:205], v199 offset:5120
	ds_read_b128 v[206:209], v199 offset:6144
	ds_read_b128 v[210:213], v199 offset:7168
	s_waitcnt vmcnt(8)
	s_waitcnt lgkmcnt(0)
	s_barrier
	s_setprio 1
	s_waitcnt lgkmcnt(0)
	v_mfma_f32_16x16x32_bf16 v[124:127], v[128:131], v[160:163], v[124:127]
	v_mfma_f32_16x16x32_bf16 v[120:123], v[136:139], v[160:163], v[120:123]
	v_mfma_f32_16x16x32_bf16 v[108:111], v[128:131], v[168:171], v[108:111]
	v_mfma_f32_16x16x32_bf16 v[104:107], v[136:139], v[168:171], v[104:107]
	v_mfma_f32_16x16x32_bf16 v[92:95], v[128:131], v[188:191], v[92:95]
	v_mfma_f32_16x16x32_bf16 v[88:91], v[136:139], v[188:191], v[88:91]
	v_mfma_f32_16x16x32_bf16 v[76:79], v[128:131], v[206:209], v[76:79]
	v_mfma_f32_16x16x32_bf16 v[72:75], v[136:139], v[206:209], v[72:75]
	v_mfma_f32_16x16x32_bf16 v[124:127], v[132:135], v[164:167], v[124:127]
	v_mfma_f32_16x16x32_bf16 v[120:123], v[140:143], v[164:167], v[120:123]
	v_mfma_f32_16x16x32_bf16 v[108:111], v[132:135], v[172:175], v[108:111]
	v_mfma_f32_16x16x32_bf16 v[104:107], v[140:143], v[172:175], v[104:107]
	v_mfma_f32_16x16x32_bf16 v[92:95], v[132:135], v[202:205], v[92:95]
	v_mfma_f32_16x16x32_bf16 v[88:91], v[140:143], v[202:205], v[88:91]
	v_mfma_f32_16x16x32_bf16 v[76:79], v[132:135], v[210:213], v[76:79]
	v_mfma_f32_16x16x32_bf16 v[72:75], v[140:143], v[210:213], v[72:75]
	s_setprio 0
	s_setprio 1
	v_mfma_f32_16x16x32_bf16 v[116:119], v[144:147], v[160:163], v[116:119]
	v_mfma_f32_16x16x32_bf16 v[112:115], v[152:155], v[160:163], v[112:115]
	v_mfma_f32_16x16x32_bf16 v[100:103], v[144:147], v[168:171], v[100:103]
	v_mfma_f32_16x16x32_bf16 v[96:99], v[152:155], v[168:171], v[96:99]
	v_mfma_f32_16x16x32_bf16 v[84:87], v[144:147], v[188:191], v[84:87]
	v_mfma_f32_16x16x32_bf16 v[80:83], v[152:155], v[188:191], v[80:83]
	v_mfma_f32_16x16x32_bf16 v[68:71], v[144:147], v[206:209], v[68:71]
	v_mfma_f32_16x16x32_bf16 v[64:67], v[152:155], v[206:209], v[64:67]
	v_mfma_f32_16x16x32_bf16 v[116:119], v[148:151], v[164:167], v[116:119]
	v_mfma_f32_16x16x32_bf16 v[112:115], v[156:159], v[164:167], v[112:115]
	v_mfma_f32_16x16x32_bf16 v[100:103], v[148:151], v[172:175], v[100:103]
	v_mfma_f32_16x16x32_bf16 v[96:99], v[156:159], v[172:175], v[96:99]
	v_mfma_f32_16x16x32_bf16 v[84:87], v[148:151], v[202:205], v[84:87]
	v_mfma_f32_16x16x32_bf16 v[80:83], v[156:159], v[202:205], v[80:83]
	v_mfma_f32_16x16x32_bf16 v[68:71], v[148:151], v[210:213], v[68:71]
	v_mfma_f32_16x16x32_bf16 v[64:67], v[156:159], v[210:213], v[64:67]
	s_setprio 0
	s_barrier
	s_add_i32 s50, s46, s3
	s_mov_b32 m0, s50
	s_nop 0
	global_load_lds_dwordx4 v176, s[30:31]
	s_add_i32 m0, s50, 0x2000
	s_add_u32 s50, s30, 0x4000
	s_addc_u32 s51, s31, 0
	s_add_i32 s52, s47, s3
	global_load_lds_dwordx4 v178, s[30:31]
	s_mov_b32 m0, s52
	s_nop 0
	global_load_lds_dwordx4 v176, s[50:51]
	s_add_i32 m0, s52, 0x2000
	s_nop 0
	global_load_lds_dwordx4 v178, s[50:51]
	s_mov_b32 m0, s33
	s_nop 0
	global_load_lds_dwordx4 v176, s[34:35]
	ds_read_b128 v[160:163], v199 offset:16384
	ds_read_b128 v[164:167], v199 offset:17408
	ds_read_b128 v[168:171], v199 offset:18432
	ds_read_b128 v[172:175], v199 offset:19456
	ds_read_b128 v[188:191], v199 offset:20480
	ds_read_b128 v[202:205], v199 offset:21504
	ds_read_b128 v[206:209], v199 offset:22528
	ds_read_b128 v[210:213], v199 offset:23552
	s_waitcnt vmcnt(7)
	s_waitcnt lgkmcnt(0)
	s_barrier
	s_setprio 1
	s_waitcnt lgkmcnt(0)
	v_mfma_f32_16x16x32_bf16 v[60:63], v[128:131], v[160:163], v[60:63]
	v_mfma_f32_16x16x32_bf16 v[56:59], v[136:139], v[160:163], v[56:59]
	v_mfma_f32_16x16x32_bf16 v[44:47], v[128:131], v[168:171], v[44:47]
	v_mfma_f32_16x16x32_bf16 v[40:43], v[136:139], v[168:171], v[40:43]
	v_mfma_f32_16x16x32_bf16 v[28:31], v[128:131], v[188:191], v[28:31]
	v_mfma_f32_16x16x32_bf16 v[24:27], v[136:139], v[188:191], v[24:27]
	v_mfma_f32_16x16x32_bf16 v[12:15], v[128:131], v[206:209], v[12:15]
	v_mfma_f32_16x16x32_bf16 v[8:11], v[136:139], v[206:209], v[8:11]
	v_mfma_f32_16x16x32_bf16 v[60:63], v[132:135], v[164:167], v[60:63]
	v_mfma_f32_16x16x32_bf16 v[56:59], v[140:143], v[164:167], v[56:59]
	v_mfma_f32_16x16x32_bf16 v[44:47], v[132:135], v[172:175], v[44:47]
	v_mfma_f32_16x16x32_bf16 v[40:43], v[140:143], v[172:175], v[40:43]
	v_mfma_f32_16x16x32_bf16 v[28:31], v[132:135], v[202:205], v[28:31]
	v_mfma_f32_16x16x32_bf16 v[24:27], v[140:143], v[202:205], v[24:27]
	v_mfma_f32_16x16x32_bf16 v[12:15], v[132:135], v[210:213], v[12:15]
	v_mfma_f32_16x16x32_bf16 v[8:11], v[140:143], v[210:213], v[8:11]
	s_setprio 0
	s_setprio 1
	v_mfma_f32_16x16x32_bf16 v[52:55], v[144:147], v[160:163], v[52:55]
	v_mfma_f32_16x16x32_bf16 v[48:51], v[152:155], v[160:163], v[48:51]
	v_mfma_f32_16x16x32_bf16 v[36:39], v[144:147], v[168:171], v[36:39]
	v_mfma_f32_16x16x32_bf16 v[32:35], v[152:155], v[168:171], v[32:35]
	v_mfma_f32_16x16x32_bf16 v[20:23], v[144:147], v[188:191], v[20:23]
	v_mfma_f32_16x16x32_bf16 v[16:19], v[152:155], v[188:191], v[16:19]
	v_mfma_f32_16x16x32_bf16 v[4:7], v[144:147], v[206:209], v[4:7]
	v_mfma_f32_16x16x32_bf16 v[0:3], v[152:155], v[206:209], v[0:3]
	v_mfma_f32_16x16x32_bf16 v[52:55], v[148:151], v[164:167], v[52:55]
	v_mfma_f32_16x16x32_bf16 v[48:51], v[156:159], v[164:167], v[48:51]
	v_mfma_f32_16x16x32_bf16 v[36:39], v[148:151], v[172:175], v[36:39]
	v_mfma_f32_16x16x32_bf16 v[32:35], v[156:159], v[172:175], v[32:35]
	v_mfma_f32_16x16x32_bf16 v[20:23], v[148:151], v[202:205], v[20:23]
	v_mfma_f32_16x16x32_bf16 v[16:19], v[156:159], v[202:205], v[16:19]
	v_mfma_f32_16x16x32_bf16 v[4:7], v[148:151], v[210:213], v[4:7]
	v_mfma_f32_16x16x32_bf16 v[0:3], v[156:159], v[210:213], v[0:3]
	s_setprio 0
	s_barrier
	s_mov_b32 m0, s36
	s_nop 0
	global_load_lds_dwordx4 v178, s[34:35]
	s_add_i32 s50, 0, 0x18000
	s_add_i32 s51, 0, 0x1c000
	v_add_u32_e32 v140, s50, v196
	v_add_u32_e32 v156, s51, v196
	s_add_u32 s34, s34, 0x4000
	s_addc_u32 s35, s35, 0
	s_mov_b32 m0, s37
	s_nop 0
	global_load_lds_dwordx4 v176, s[34:35]
	s_mov_b32 m0, s38
	s_nop 0
	global_load_lds_dwordx4 v178, s[34:35]
	ds_read_b128 v[128:131], v140
	ds_read_b128 v[132:135], v140 offset:1024
	ds_read_b128 v[136:139], v140 offset:2048
	ds_read_b128 v[140:143], v140 offset:3072
	ds_read_b128 v[144:147], v156
	ds_read_b128 v[148:151], v156 offset:1024
	ds_read_b128 v[152:155], v156 offset:2048
	ds_read_b128 v[156:159], v156 offset:3072
	ds_read_b128 v[160:163], v199 offset:32768
	ds_read_b128 v[164:167], v199 offset:33792
	ds_read_b128 v[168:171], v199 offset:34816
	ds_read_b128 v[172:175], v199 offset:35840
	ds_read_b128 v[188:191], v199 offset:36864
	ds_read_b128 v[202:205], v199 offset:37888
	ds_read_b128 v[206:209], v199 offset:38912
	ds_read_b128 v[210:213], v199 offset:39936
	s_waitcnt vmcnt(8)
	s_waitcnt lgkmcnt(0)
	s_barrier
	s_setprio 1
	s_waitcnt lgkmcnt(0)
	v_mfma_f32_16x16x32_bf16 v[124:127], v[128:131], v[160:163], v[124:127]
	v_mfma_f32_16x16x32_bf16 v[120:123], v[136:139], v[160:163], v[120:123]
	v_mfma_f32_16x16x32_bf16 v[108:111], v[128:131], v[168:171], v[108:111]
	v_mfma_f32_16x16x32_bf16 v[104:107], v[136:139], v[168:171], v[104:107]
	v_mfma_f32_16x16x32_bf16 v[92:95], v[128:131], v[188:191], v[92:95]
	v_mfma_f32_16x16x32_bf16 v[88:91], v[136:139], v[188:191], v[88:91]
	v_mfma_f32_16x16x32_bf16 v[76:79], v[128:131], v[206:209], v[76:79]
	v_mfma_f32_16x16x32_bf16 v[72:75], v[136:139], v[206:209], v[72:75]
	v_mfma_f32_16x16x32_bf16 v[124:127], v[132:135], v[164:167], v[124:127]
	v_mfma_f32_16x16x32_bf16 v[120:123], v[140:143], v[164:167], v[120:123]
	v_mfma_f32_16x16x32_bf16 v[108:111], v[132:135], v[172:175], v[108:111]
	v_mfma_f32_16x16x32_bf16 v[104:107], v[140:143], v[172:175], v[104:107]
	v_mfma_f32_16x16x32_bf16 v[92:95], v[132:135], v[202:205], v[92:95]
	v_mfma_f32_16x16x32_bf16 v[88:91], v[140:143], v[202:205], v[88:91]
	v_mfma_f32_16x16x32_bf16 v[76:79], v[132:135], v[210:213], v[76:79]
	v_mfma_f32_16x16x32_bf16 v[72:75], v[140:143], v[210:213], v[72:75]
	s_setprio 0
	s_setprio 1
	v_mfma_f32_16x16x32_bf16 v[116:119], v[144:147], v[160:163], v[116:119]
	v_mfma_f32_16x16x32_bf16 v[112:115], v[152:155], v[160:163], v[112:115]
	v_mfma_f32_16x16x32_bf16 v[100:103], v[144:147], v[168:171], v[100:103]
	v_mfma_f32_16x16x32_bf16 v[96:99], v[152:155], v[168:171], v[96:99]
	v_mfma_f32_16x16x32_bf16 v[84:87], v[144:147], v[188:191], v[84:87]
	v_mfma_f32_16x16x32_bf16 v[80:83], v[152:155], v[188:191], v[80:83]
	v_mfma_f32_16x16x32_bf16 v[68:71], v[144:147], v[206:209], v[68:71]
	v_mfma_f32_16x16x32_bf16 v[64:67], v[152:155], v[206:209], v[64:67]
	v_mfma_f32_16x16x32_bf16 v[116:119], v[148:151], v[164:167], v[116:119]
	v_mfma_f32_16x16x32_bf16 v[112:115], v[156:159], v[164:167], v[112:115]
	v_mfma_f32_16x16x32_bf16 v[100:103], v[148:151], v[172:175], v[100:103]
	v_mfma_f32_16x16x32_bf16 v[96:99], v[156:159], v[172:175], v[96:99]
	v_mfma_f32_16x16x32_bf16 v[84:87], v[148:151], v[202:205], v[84:87]
	v_mfma_f32_16x16x32_bf16 v[80:83], v[156:159], v[202:205], v[80:83]
	v_mfma_f32_16x16x32_bf16 v[68:71], v[148:151], v[210:213], v[68:71]
	v_mfma_f32_16x16x32_bf16 v[64:67], v[156:159], v[210:213], v[64:67]
	s_setprio 0
	s_barrier
	s_add_u32 s34, s30, 0x8000
	s_addc_u32 s35, s31, 0
	s_add_i32 s50, s50, s3
	s_mov_b32 m0, s50
	s_nop 0
	global_load_lds_dwordx4 v176, s[34:35]
	s_add_i32 m0, s50, 0x2000
	s_add_u32 s30, s30, 0xc000
	s_addc_u32 s31, s31, 0
	global_load_lds_dwordx4 v178, s[34:35]
	s_add_i32 s34, s51, s3
	s_mov_b32 m0, s34
	s_nop 0
	global_load_lds_dwordx4 v176, s[30:31]
	s_add_i32 m0, s34, 0x2000
	s_nop 0
	global_load_lds_dwordx4 v178, s[30:31]
	s_mov_b32 m0, s42
	s_nop 0
	global_load_lds_dwordx4 v176, s[28:29]
	s_mov_b32 m0, s43
	s_nop 0
	global_load_lds_dwordx4 v178, s[28:29]
	ds_read_b128 v[160:163], v199 offset:49152
	ds_read_b128 v[164:167], v199 offset:50176
	ds_read_b128 v[168:171], v199 offset:51200
	ds_read_b128 v[172:175], v199 offset:52224
	ds_read_b128 v[188:191], v199 offset:53248
	ds_read_b128 v[202:205], v199 offset:54272
	ds_read_b128 v[206:209], v199 offset:55296
	ds_read_b128 v[210:213], v199 offset:56320
	s_waitcnt vmcnt(8)
	s_waitcnt lgkmcnt(0)
	s_barrier
	s_setprio 1
	s_waitcnt lgkmcnt(0)
	v_mfma_f32_16x16x32_bf16 v[60:63], v[128:131], v[160:163], v[60:63]
	v_mfma_f32_16x16x32_bf16 v[56:59], v[136:139], v[160:163], v[56:59]
	v_mfma_f32_16x16x32_bf16 v[44:47], v[128:131], v[168:171], v[44:47]
	v_mfma_f32_16x16x32_bf16 v[40:43], v[136:139], v[168:171], v[40:43]
	v_mfma_f32_16x16x32_bf16 v[28:31], v[128:131], v[188:191], v[28:31]
	v_mfma_f32_16x16x32_bf16 v[24:27], v[136:139], v[188:191], v[24:27]
	v_mfma_f32_16x16x32_bf16 v[12:15], v[128:131], v[206:209], v[12:15]
	v_mfma_f32_16x16x32_bf16 v[8:11], v[136:139], v[206:209], v[8:11]
	v_mfma_f32_16x16x32_bf16 v[60:63], v[132:135], v[164:167], v[60:63]
	v_mfma_f32_16x16x32_bf16 v[56:59], v[140:143], v[164:167], v[56:59]
	v_mfma_f32_16x16x32_bf16 v[44:47], v[132:135], v[172:175], v[44:47]
	v_mfma_f32_16x16x32_bf16 v[40:43], v[140:143], v[172:175], v[40:43]
	v_mfma_f32_16x16x32_bf16 v[28:31], v[132:135], v[202:205], v[28:31]
	v_mfma_f32_16x16x32_bf16 v[24:27], v[140:143], v[202:205], v[24:27]
	v_mfma_f32_16x16x32_bf16 v[12:15], v[132:135], v[210:213], v[12:15]
	v_mfma_f32_16x16x32_bf16 v[8:11], v[140:143], v[210:213], v[8:11]
	s_setprio 0
	s_setprio 1
	v_mfma_f32_16x16x32_bf16 v[52:55], v[144:147], v[160:163], v[52:55]
	v_mfma_f32_16x16x32_bf16 v[48:51], v[152:155], v[160:163], v[48:51]
	v_mfma_f32_16x16x32_bf16 v[36:39], v[144:147], v[168:171], v[36:39]
	v_mfma_f32_16x16x32_bf16 v[32:35], v[152:155], v[168:171], v[32:35]
	v_mfma_f32_16x16x32_bf16 v[20:23], v[144:147], v[188:191], v[20:23]
	v_mfma_f32_16x16x32_bf16 v[16:19], v[152:155], v[188:191], v[16:19]
	v_mfma_f32_16x16x32_bf16 v[4:7], v[144:147], v[206:209], v[4:7]
	v_mfma_f32_16x16x32_bf16 v[0:3], v[152:155], v[206:209], v[0:3]
	v_mfma_f32_16x16x32_bf16 v[52:55], v[148:151], v[164:167], v[52:55]
	v_mfma_f32_16x16x32_bf16 v[48:51], v[156:159], v[164:167], v[48:51]
	v_mfma_f32_16x16x32_bf16 v[36:39], v[148:151], v[172:175], v[36:39]
	v_mfma_f32_16x16x32_bf16 v[32:35], v[156:159], v[172:175], v[32:35]
	v_mfma_f32_16x16x32_bf16 v[20:23], v[148:151], v[202:205], v[20:23]
	v_mfma_f32_16x16x32_bf16 v[16:19], v[156:159], v[202:205], v[16:19]
	v_mfma_f32_16x16x32_bf16 v[4:7], v[148:151], v[210:213], v[4:7]
	v_mfma_f32_16x16x32_bf16 v[0:3], v[156:159], v[210:213], v[0:3]
	s_setprio 0
	s_barrier
	s_add_i32 s49, s49, 2
	s_add_u32 s26, s26, 0x10000
	s_addc_u32 s27, s27, 0
	s_add_u32 s25, s25, 0x10000
	s_addc_u32 s48, s48, 0
	s_cmp_gt_u32 s49, 61
	s_cbranch_scc0 .LBB0_469
	s_and_b64 vcc, exec, s[12:13]
	s_cbranch_vccz .LBB0_472
	s_barrier

.LBB0_640:
	s_add_u32 s22, s20, 0x4000
	s_addc_u32 s23, s21, 0
	s_cmp_eq_u32 s51, 60
	s_cselect_b32 s26, s19, s22
	s_cselect_b32 s27, s11, s23
	s_cselect_b32 s24, s48, s49
	s_cselect_b32 s25, s13, s50
	s_add_u32 s22, s26, 0x8000
	s_addc_u32 s23, s27, 0
	s_add_i32 m0, s30, 0xc000
	s_nop 0
	global_load_lds_dwordx4 v160, s[20:21]
	s_add_i32 m0, s30, 0xe000
	s_nop 0
	global_load_lds_dwordx4 v162, s[20:21]
	ds_read_b128 v[56:59], v179
	ds_read_b128 v[60:63], v179 offset:1024
	ds_read_b128 v[64:67], v179 offset:2048
	ds_read_b128 v[68:71], v179 offset:3072
	ds_read_b128 v[144:147], v180
	ds_read_b128 v[148:151], v180 offset:1024
	ds_read_b128 v[152:155], v180 offset:2048
	ds_read_b128 v[156:159], v180 offset:3072
	ds_read_b128 v[172:175], v181
	ds_read_b128 v[182:185], v181 offset:1024
	ds_read_b128 v[186:189], v181 offset:2048
	ds_read_b128 v[190:193], v181 offset:3072
	ds_read_b128 v[196:199], v181 offset:4096
	ds_read_b128 v[200:203], v181 offset:5120
	ds_read_b128 v[204:207], v181 offset:6144
	ds_read_b128 v[208:211], v181 offset:7168
	s_waitcnt vmcnt(8)
	s_waitcnt lgkmcnt(0)
	s_barrier
	s_setprio 1
	s_waitcnt lgkmcnt(0)
	v_mfma_f32_16x16x32_bf16 v[140:143], v[56:59], v[172:175], v[140:143]
	v_mfma_f32_16x16x32_bf16 v[136:139], v[64:67], v[172:175], v[136:139]
	v_mfma_f32_16x16x32_bf16 v[124:127], v[56:59], v[186:189], v[124:127]
	v_mfma_f32_16x16x32_bf16 v[120:123], v[64:67], v[186:189], v[120:123]
	v_mfma_f32_16x16x32_bf16 v[108:111], v[56:59], v[196:199], v[108:111]
	v_mfma_f32_16x16x32_bf16 v[104:107], v[64:67], v[196:199], v[104:107]
	v_mfma_f32_16x16x32_bf16 v[92:95], v[56:59], v[204:207], v[92:95]
	v_mfma_f32_16x16x32_bf16 v[88:91], v[64:67], v[204:207], v[88:91]
	v_mfma_f32_16x16x32_bf16 v[140:143], v[60:63], v[182:185], v[140:143]
	v_mfma_f32_16x16x32_bf16 v[136:139], v[68:71], v[182:185], v[136:139]
	v_mfma_f32_16x16x32_bf16 v[124:127], v[60:63], v[190:193], v[124:127]
	v_mfma_f32_16x16x32_bf16 v[120:123], v[68:71], v[190:193], v[120:123]
	v_mfma_f32_16x16x32_bf16 v[108:111], v[60:63], v[200:203], v[108:111]
	v_mfma_f32_16x16x32_bf16 v[104:107], v[68:71], v[200:203], v[104:107]
	v_mfma_f32_16x16x32_bf16 v[92:95], v[60:63], v[208:211], v[92:95]
	v_mfma_f32_16x16x32_bf16 v[88:91], v[68:71], v[208:211], v[88:91]
	s_setprio 0
	s_setprio 1
	v_mfma_f32_16x16x32_bf16 v[132:135], v[144:147], v[172:175], v[132:135]
	v_mfma_f32_16x16x32_bf16 v[128:131], v[152:155], v[172:175], v[128:131]
	v_mfma_f32_16x16x32_bf16 v[116:119], v[144:147], v[186:189], v[116:119]
	v_mfma_f32_16x16x32_bf16 v[112:115], v[152:155], v[186:189], v[112:115]
	v_mfma_f32_16x16x32_bf16 v[100:103], v[144:147], v[196:199], v[100:103]
	v_mfma_f32_16x16x32_bf16 v[96:99], v[152:155], v[196:199], v[96:99]
	v_mfma_f32_16x16x32_bf16 v[84:87], v[144:147], v[204:207], v[84:87]
	v_mfma_f32_16x16x32_bf16 v[80:83], v[152:155], v[204:207], v[80:83]
	v_mfma_f32_16x16x32_bf16 v[132:135], v[148:151], v[182:185], v[132:135]
	v_mfma_f32_16x16x32_bf16 v[128:131], v[156:159], v[182:185], v[128:131]
	v_mfma_f32_16x16x32_bf16 v[116:119], v[148:151], v[190:193], v[116:119]
	v_mfma_f32_16x16x32_bf16 v[112:115], v[156:159], v[190:193], v[112:115]
	v_mfma_f32_16x16x32_bf16 v[100:103], v[148:151], v[200:203], v[100:103]
	v_mfma_f32_16x16x32_bf16 v[96:99], v[156:159], v[200:203], v[96:99]
	v_mfma_f32_16x16x32_bf16 v[84:87], v[148:151], v[208:211], v[84:87]
	v_mfma_f32_16x16x32_bf16 v[80:83], v[156:159], v[208:211], v[80:83]
	s_setprio 0
	s_barrier
	s_add_i32 s52, s46, s3
	s_mov_b32 m0, s52
	s_nop 0
	global_load_lds_dwordx4 v160, s[24:25]
	s_add_i32 m0, s52, 0x2000
	s_add_u32 s52, s24, 0x4000
	s_addc_u32 s53, s25, 0
	s_add_i32 s54, s47, s3
	global_load_lds_dwordx4 v162, s[24:25]
	s_mov_b32 m0, s54
	s_nop 0
	global_load_lds_dwordx4 v160, s[52:53]
	s_add_i32 m0, s54, 0x2000
	s_nop 0
	global_load_lds_dwordx4 v162, s[52:53]
	s_mov_b32 m0, s30
	s_nop 0
	global_load_lds_dwordx4 v160, s[26:27]
	ds_read_b128 v[172:175], v181 offset:16384
	ds_read_b128 v[182:185], v181 offset:17408
	ds_read_b128 v[186:189], v181 offset:18432
	ds_read_b128 v[190:193], v181 offset:19456
	ds_read_b128 v[196:199], v181 offset:20480
	ds_read_b128 v[200:203], v181 offset:21504
	ds_read_b128 v[204:207], v181 offset:22528
	ds_read_b128 v[208:211], v181 offset:23552
	s_waitcnt vmcnt(7)
	s_waitcnt lgkmcnt(0)
	s_barrier
	s_setprio 1
	s_waitcnt lgkmcnt(0)
	v_mfma_f32_16x16x32_bf16 v[76:79], v[56:59], v[172:175], v[76:79]
	v_mfma_f32_16x16x32_bf16 v[72:75], v[64:67], v[172:175], v[72:75]
	v_mfma_f32_16x16x32_bf16 v[44:47], v[56:59], v[186:189], v[44:47]
	v_mfma_f32_16x16x32_bf16 v[40:43], v[64:67], v[186:189], v[40:43]
	v_mfma_f32_16x16x32_bf16 v[28:31], v[56:59], v[196:199], v[28:31]
	v_mfma_f32_16x16x32_bf16 v[24:27], v[64:67], v[196:199], v[24:27]
	v_mfma_f32_16x16x32_bf16 v[12:15], v[56:59], v[204:207], v[12:15]
	v_mfma_f32_16x16x32_bf16 v[8:11], v[64:67], v[204:207], v[8:11]
	v_mfma_f32_16x16x32_bf16 v[76:79], v[60:63], v[182:185], v[76:79]
	v_mfma_f32_16x16x32_bf16 v[72:75], v[68:71], v[182:185], v[72:75]
	v_mfma_f32_16x16x32_bf16 v[44:47], v[60:63], v[190:193], v[44:47]
	v_mfma_f32_16x16x32_bf16 v[40:43], v[68:71], v[190:193], v[40:43]
	v_mfma_f32_16x16x32_bf16 v[28:31], v[60:63], v[200:203], v[28:31]
	v_mfma_f32_16x16x32_bf16 v[24:27], v[68:71], v[200:203], v[24:27]
	v_mfma_f32_16x16x32_bf16 v[12:15], v[60:63], v[208:211], v[12:15]
	v_mfma_f32_16x16x32_bf16 v[8:11], v[68:71], v[208:211], v[8:11]
	s_setprio 0
	s_setprio 1
	v_mfma_f32_16x16x32_bf16 v[52:55], v[144:147], v[172:175], v[52:55]
	v_mfma_f32_16x16x32_bf16 v[48:51], v[152:155], v[172:175], v[48:51]
	v_mfma_f32_16x16x32_bf16 v[36:39], v[144:147], v[186:189], v[36:39]
	v_mfma_f32_16x16x32_bf16 v[32:35], v[152:155], v[186:189], v[32:35]
	v_mfma_f32_16x16x32_bf16 v[20:23], v[144:147], v[196:199], v[20:23]
	v_mfma_f32_16x16x32_bf16 v[16:19], v[152:155], v[196:199], v[16:19]
	v_mfma_f32_16x16x32_bf16 v[4:7], v[144:147], v[204:207], v[4:7]
	v_mfma_f32_16x16x32_bf16 v[0:3], v[152:155], v[204:207], v[0:3]
	v_mfma_f32_16x16x32_bf16 v[52:55], v[148:151], v[182:185], v[52:55]
	v_mfma_f32_16x16x32_bf16 v[48:51], v[156:159], v[182:185], v[48:51]
	v_mfma_f32_16x16x32_bf16 v[36:39], v[148:151], v[190:193], v[36:39]
	v_mfma_f32_16x16x32_bf16 v[32:35], v[156:159], v[190:193], v[32:35]
	v_mfma_f32_16x16x32_bf16 v[20:23], v[148:151], v[200:203], v[20:23]
	v_mfma_f32_16x16x32_bf16 v[16:19], v[156:159], v[200:203], v[16:19]
	v_mfma_f32_16x16x32_bf16 v[4:7], v[148:151], v[208:211], v[4:7]
	v_mfma_f32_16x16x32_bf16 v[0:3], v[156:159], v[208:211], v[0:3]
	s_setprio 0
	s_barrier
	s_mov_b32 m0, s31
	s_nop 0
	global_load_lds_dwordx4 v162, s[26:27]
	s_add_i32 s52, 0, 0x18000
	s_add_i32 s53, 0, 0x1c000
	v_add_u32_e32 v68, s52, v178
	v_add_u32_e32 v156, s53, v178
	s_add_u32 s26, s26, 0x4000
	s_addc_u32 s27, s27, 0
	s_mov_b32 m0, s33
	s_nop 0
	global_load_lds_dwordx4 v160, s[26:27]
	s_mov_b32 m0, s34
	s_nop 0
	global_load_lds_dwordx4 v162, s[26:27]
	ds_read_b128 v[56:59], v68
	ds_read_b128 v[60:63], v68 offset:1024
	ds_read_b128 v[64:67], v68 offset:2048
	ds_read_b128 v[68:71], v68 offset:3072
	ds_read_b128 v[144:147], v156
	ds_read_b128 v[148:151], v156 offset:1024
	ds_read_b128 v[152:155], v156 offset:2048
	ds_read_b128 v[156:159], v156 offset:3072
	ds_read_b128 v[172:175], v181 offset:32768
	ds_read_b128 v[182:185], v181 offset:33792
	ds_read_b128 v[186:189], v181 offset:34816
	ds_read_b128 v[190:193], v181 offset:35840
	ds_read_b128 v[196:199], v181 offset:36864
	ds_read_b128 v[200:203], v181 offset:37888
	ds_read_b128 v[204:207], v181 offset:38912
	ds_read_b128 v[208:211], v181 offset:39936
	s_waitcnt vmcnt(8)
	s_waitcnt lgkmcnt(0)
	s_barrier
	s_setprio 1
	s_waitcnt lgkmcnt(0)
	v_mfma_f32_16x16x32_bf16 v[140:143], v[56:59], v[172:175], v[140:143]
	v_mfma_f32_16x16x32_bf16 v[136:139], v[64:67], v[172:175], v[136:139]
	v_mfma_f32_16x16x32_bf16 v[124:127], v[56:59], v[186:189], v[124:127]
	v_mfma_f32_16x16x32_bf16 v[120:123], v[64:67], v[186:189], v[120:123]
	v_mfma_f32_16x16x32_bf16 v[108:111], v[56:59], v[196:199], v[108:111]
	v_mfma_f32_16x16x32_bf16 v[104:107], v[64:67], v[196:199], v[104:107]
	v_mfma_f32_16x16x32_bf16 v[92:95], v[56:59], v[204:207], v[92:95]
	v_mfma_f32_16x16x32_bf16 v[88:91], v[64:67], v[204:207], v[88:91]
	v_mfma_f32_16x16x32_bf16 v[140:143], v[60:63], v[182:185], v[140:143]
	v_mfma_f32_16x16x32_bf16 v[136:139], v[68:71], v[182:185], v[136:139]
	v_mfma_f32_16x16x32_bf16 v[124:127], v[60:63], v[190:193], v[124:127]
	v_mfma_f32_16x16x32_bf16 v[120:123], v[68:71], v[190:193], v[120:123]
	v_mfma_f32_16x16x32_bf16 v[108:111], v[60:63], v[200:203], v[108:111]
	v_mfma_f32_16x16x32_bf16 v[104:107], v[68:71], v[200:203], v[104:107]
	v_mfma_f32_16x16x32_bf16 v[92:95], v[60:63], v[208:211], v[92:95]
	v_mfma_f32_16x16x32_bf16 v[88:91], v[68:71], v[208:211], v[88:91]
	s_setprio 0
	s_setprio 1
	v_mfma_f32_16x16x32_bf16 v[132:135], v[144:147], v[172:175], v[132:135]
	v_mfma_f32_16x16x32_bf16 v[128:131], v[152:155], v[172:175], v[128:131]
	v_mfma_f32_16x16x32_bf16 v[116:119], v[144:147], v[186:189], v[116:119]
	v_mfma_f32_16x16x32_bf16 v[112:115], v[152:155], v[186:189], v[112:115]
	v_mfma_f32_16x16x32_bf16 v[100:103], v[144:147], v[196:199], v[100:103]
	v_mfma_f32_16x16x32_bf16 v[96:99], v[152:155], v[196:199], v[96:99]
	v_mfma_f32_16x16x32_bf16 v[84:87], v[144:147], v[204:207], v[84:87]
	v_mfma_f32_16x16x32_bf16 v[80:83], v[152:155], v[204:207], v[80:83]
	v_mfma_f32_16x16x32_bf16 v[132:135], v[148:151], v[182:185], v[132:135]
	v_mfma_f32_16x16x32_bf16 v[128:131], v[156:159], v[182:185], v[128:131]
	v_mfma_f32_16x16x32_bf16 v[116:119], v[148:151], v[190:193], v[116:119]
	v_mfma_f32_16x16x32_bf16 v[112:115], v[156:159], v[190:193], v[112:115]
	v_mfma_f32_16x16x32_bf16 v[100:103], v[148:151], v[200:203], v[100:103]
	v_mfma_f32_16x16x32_bf16 v[96:99], v[156:159], v[200:203], v[96:99]
	v_mfma_f32_16x16x32_bf16 v[84:87], v[148:151], v[208:211], v[84:87]
	v_mfma_f32_16x16x32_bf16 v[80:83], v[156:159], v[208:211], v[80:83]
	s_setprio 0
	s_barrier
	s_add_u32 s26, s24, 0x8000
	s_addc_u32 s27, s25, 0
	s_add_i32 s52, s52, s3
	s_mov_b32 m0, s52
	s_nop 0
	global_load_lds_dwordx4 v160, s[26:27]
	s_add_i32 m0, s52, 0x2000
	s_add_u32 s24, s24, 0xc000
	s_addc_u32 s25, s25, 0
	global_load_lds_dwordx4 v162, s[26:27]
	s_add_i32 s26, s53, s3
	s_mov_b32 m0, s26
	s_nop 0
	global_load_lds_dwordx4 v160, s[24:25]
	s_add_i32 m0, s26, 0x2000
	s_nop 0
	global_load_lds_dwordx4 v162, s[24:25]
	s_mov_b32 m0, s39
	s_nop 0
	global_load_lds_dwordx4 v160, s[22:23]
	s_mov_b32 m0, s40
	s_nop 0
	global_load_lds_dwordx4 v162, s[22:23]
	ds_read_b128 v[172:175], v181 offset:49152
	ds_read_b128 v[182:185], v181 offset:50176
	ds_read_b128 v[186:189], v181 offset:51200
	ds_read_b128 v[190:193], v181 offset:52224
	ds_read_b128 v[196:199], v181 offset:53248
	ds_read_b128 v[200:203], v181 offset:54272
	ds_read_b128 v[204:207], v181 offset:55296
	ds_read_b128 v[208:211], v181 offset:56320
	s_waitcnt vmcnt(8)
	s_waitcnt lgkmcnt(0)
	s_barrier
	s_setprio 1
	s_waitcnt lgkmcnt(0)
	v_mfma_f32_16x16x32_bf16 v[76:79], v[56:59], v[172:175], v[76:79]
	v_mfma_f32_16x16x32_bf16 v[72:75], v[64:67], v[172:175], v[72:75]
	v_mfma_f32_16x16x32_bf16 v[44:47], v[56:59], v[186:189], v[44:47]
	v_mfma_f32_16x16x32_bf16 v[40:43], v[64:67], v[186:189], v[40:43]
	v_mfma_f32_16x16x32_bf16 v[28:31], v[56:59], v[196:199], v[28:31]
	v_mfma_f32_16x16x32_bf16 v[24:27], v[64:67], v[196:199], v[24:27]
	v_mfma_f32_16x16x32_bf16 v[12:15], v[56:59], v[204:207], v[12:15]
	v_mfma_f32_16x16x32_bf16 v[8:11], v[64:67], v[204:207], v[8:11]
	v_mfma_f32_16x16x32_bf16 v[76:79], v[60:63], v[182:185], v[76:79]
	v_mfma_f32_16x16x32_bf16 v[72:75], v[68:71], v[182:185], v[72:75]
	v_mfma_f32_16x16x32_bf16 v[44:47], v[60:63], v[190:193], v[44:47]
	v_mfma_f32_16x16x32_bf16 v[40:43], v[68:71], v[190:193], v[40:43]
	v_mfma_f32_16x16x32_bf16 v[28:31], v[60:63], v[200:203], v[28:31]
	v_mfma_f32_16x16x32_bf16 v[24:27], v[68:71], v[200:203], v[24:27]
	v_mfma_f32_16x16x32_bf16 v[12:15], v[60:63], v[208:211], v[12:15]
	v_mfma_f32_16x16x32_bf16 v[8:11], v[68:71], v[208:211], v[8:11]
	s_setprio 0
	s_setprio 1
	v_mfma_f32_16x16x32_bf16 v[52:55], v[144:147], v[172:175], v[52:55]
	v_mfma_f32_16x16x32_bf16 v[48:51], v[152:155], v[172:175], v[48:51]
	v_mfma_f32_16x16x32_bf16 v[36:39], v[144:147], v[186:189], v[36:39]
	v_mfma_f32_16x16x32_bf16 v[32:35], v[152:155], v[186:189], v[32:35]
	v_mfma_f32_16x16x32_bf16 v[20:23], v[144:147], v[196:199], v[20:23]
	v_mfma_f32_16x16x32_bf16 v[16:19], v[152:155], v[196:199], v[16:19]
	v_mfma_f32_16x16x32_bf16 v[4:7], v[144:147], v[204:207], v[4:7]
	v_mfma_f32_16x16x32_bf16 v[0:3], v[152:155], v[204:207], v[0:3]
	v_mfma_f32_16x16x32_bf16 v[52:55], v[148:151], v[182:185], v[52:55]
	v_mfma_f32_16x16x32_bf16 v[48:51], v[156:159], v[182:185], v[48:51]
	v_mfma_f32_16x16x32_bf16 v[36:39], v[148:151], v[190:193], v[36:39]
	v_mfma_f32_16x16x32_bf16 v[32:35], v[156:159], v[190:193], v[32:35]
	v_mfma_f32_16x16x32_bf16 v[20:23], v[148:151], v[200:203], v[20:23]
	v_mfma_f32_16x16x32_bf16 v[16:19], v[156:159], v[200:203], v[16:19]
	v_mfma_f32_16x16x32_bf16 v[4:7], v[148:151], v[208:211], v[4:7]
	v_mfma_f32_16x16x32_bf16 v[0:3], v[156:159], v[208:211], v[0:3]
	s_setprio 0
	s_barrier
	s_add_i32 s51, s51, 2
	s_add_u32 s20, s20, 0x10000
	s_addc_u32 s21, s21, 0
	s_add_u32 s49, s49, 0x10000
	s_addc_u32 s50, s50, 0
	s_cmp_gt_u32 s51, 61
	s_cbranch_scc0 .LBB0_640
	s_and_b64 vcc, exec, s[6:7]
	s_cbranch_vccz .LBB0_643
	s_barrier

.LBB0_716:
	s_add_u32 s20, s18, 0x4000
	s_addc_u32 s21, s19, 0
	s_cmp_eq_u32 s48, 60
	s_cselect_b32 s24, s44, s20
	s_cselect_b32 s25, s9, s21
	s_cselect_b32 s22, s45, s46
	s_cselect_b32 s23, s11, s47
	s_add_u32 s20, s24, 0x8000
	s_addc_u32 s21, s25, 0
	s_add_i32 m0, s28, 0xc000
	s_nop 0
	global_load_lds_dwordx4 v128, s[18:19]
	s_add_i32 m0, s28, 0xe000
	s_nop 0
	global_load_lds_dwordx4 v130, s[18:19]
	ds_read_b128 v[138:141], v145
	ds_read_b128 v[148:151], v145 offset:1024
	ds_read_b128 v[152:155], v145 offset:2048
	ds_read_b128 v[156:159], v145 offset:3072
	ds_read_b128 v[160:163], v146
	ds_read_b128 v[164:167], v146 offset:1024
	ds_read_b128 v[168:171], v146 offset:2048
	ds_read_b128 v[172:175], v146 offset:3072
	ds_read_b128 v[176:179], v147
	ds_read_b128 v[180:183], v147 offset:1024
	ds_read_b128 v[184:187], v147 offset:2048
	ds_read_b128 v[188:191], v147 offset:3072
	ds_read_b128 v[192:195], v147 offset:4096
	ds_read_b128 v[196:199], v147 offset:5120
	ds_read_b128 v[200:203], v147 offset:6144
	ds_read_b128 v[204:207], v147 offset:7168
	s_waitcnt vmcnt(8)
	s_waitcnt lgkmcnt(0)
	s_barrier
	s_setprio 1
	s_waitcnt lgkmcnt(0)
	v_mfma_f32_16x16x32_bf16 v[124:127], v[138:141], v[176:179], v[124:127]
	v_mfma_f32_16x16x32_bf16 v[120:123], v[152:155], v[176:179], v[120:123]
	v_mfma_f32_16x16x32_bf16 v[116:119], v[138:141], v[184:187], v[116:119]
	v_mfma_f32_16x16x32_bf16 v[104:107], v[152:155], v[184:187], v[104:107]
	v_mfma_f32_16x16x32_bf16 v[92:95], v[138:141], v[192:195], v[92:95]
	v_mfma_f32_16x16x32_bf16 v[88:91], v[152:155], v[192:195], v[88:91]
	v_mfma_f32_16x16x32_bf16 v[84:87], v[138:141], v[200:203], v[84:87]
	v_mfma_f32_16x16x32_bf16 v[72:75], v[152:155], v[200:203], v[72:75]
	v_mfma_f32_16x16x32_bf16 v[124:127], v[148:151], v[180:183], v[124:127]
	v_mfma_f32_16x16x32_bf16 v[120:123], v[156:159], v[180:183], v[120:123]
	v_mfma_f32_16x16x32_bf16 v[116:119], v[148:151], v[188:191], v[116:119]
	v_mfma_f32_16x16x32_bf16 v[104:107], v[156:159], v[188:191], v[104:107]
	v_mfma_f32_16x16x32_bf16 v[92:95], v[148:151], v[196:199], v[92:95]
	v_mfma_f32_16x16x32_bf16 v[88:91], v[156:159], v[196:199], v[88:91]
	v_mfma_f32_16x16x32_bf16 v[84:87], v[148:151], v[204:207], v[84:87]
	v_mfma_f32_16x16x32_bf16 v[72:75], v[156:159], v[204:207], v[72:75]
	s_setprio 0
	s_setprio 1
	v_mfma_f32_16x16x32_bf16 v[112:115], v[160:163], v[176:179], v[112:115]
	v_mfma_f32_16x16x32_bf16 v[108:111], v[168:171], v[176:179], v[108:111]
	v_mfma_f32_16x16x32_bf16 v[100:103], v[160:163], v[184:187], v[100:103]
	v_mfma_f32_16x16x32_bf16 v[96:99], v[168:171], v[184:187], v[96:99]
	v_mfma_f32_16x16x32_bf16 v[80:83], v[160:163], v[192:195], v[80:83]
	v_mfma_f32_16x16x32_bf16 v[76:79], v[168:171], v[192:195], v[76:79]
	v_mfma_f32_16x16x32_bf16 v[68:71], v[160:163], v[200:203], v[68:71]
	v_mfma_f32_16x16x32_bf16 v[64:67], v[168:171], v[200:203], v[64:67]
	v_mfma_f32_16x16x32_bf16 v[112:115], v[164:167], v[180:183], v[112:115]
	v_mfma_f32_16x16x32_bf16 v[108:111], v[172:175], v[180:183], v[108:111]
	v_mfma_f32_16x16x32_bf16 v[100:103], v[164:167], v[188:191], v[100:103]
	v_mfma_f32_16x16x32_bf16 v[96:99], v[172:175], v[188:191], v[96:99]
	v_mfma_f32_16x16x32_bf16 v[80:83], v[164:167], v[196:199], v[80:83]
	v_mfma_f32_16x16x32_bf16 v[76:79], v[172:175], v[196:199], v[76:79]
	v_mfma_f32_16x16x32_bf16 v[68:71], v[164:167], v[204:207], v[68:71]
	v_mfma_f32_16x16x32_bf16 v[64:67], v[172:175], v[204:207], v[64:67]
	s_setprio 0
	s_barrier
	s_add_i32 s49, s42, s3
	s_mov_b32 m0, s49
	s_nop 0
	global_load_lds_dwordx4 v128, s[22:23]
	s_add_i32 m0, s49, 0x2000
	s_add_u32 s50, s22, 0x4000
	s_addc_u32 s51, s23, 0
	s_add_i32 s49, s43, s3
	global_load_lds_dwordx4 v130, s[22:23]
	s_mov_b32 m0, s49
	s_nop 0
	global_load_lds_dwordx4 v128, s[50:51]
	s_add_i32 m0, s49, 0x2000
	s_nop 0
	global_load_lds_dwordx4 v130, s[50:51]
	s_mov_b32 m0, s28
	s_nop 0
	global_load_lds_dwordx4 v128, s[24:25]
	ds_read_b128 v[176:179], v147 offset:16384
	ds_read_b128 v[180:183], v147 offset:17408
	ds_read_b128 v[184:187], v147 offset:18432
	ds_read_b128 v[188:191], v147 offset:19456
	ds_read_b128 v[192:195], v147 offset:20480
	ds_read_b128 v[196:199], v147 offset:21504
	ds_read_b128 v[200:203], v147 offset:22528
	ds_read_b128 v[204:207], v147 offset:23552
	s_waitcnt vmcnt(7)
	s_waitcnt lgkmcnt(0)
	s_barrier
	s_setprio 1
	s_waitcnt lgkmcnt(0)
	v_mfma_f32_16x16x32_bf16 v[60:63], v[138:141], v[176:179], v[60:63]
	v_mfma_f32_16x16x32_bf16 v[56:59], v[152:155], v[176:179], v[56:59]
	v_mfma_f32_16x16x32_bf16 v[48:51], v[138:141], v[184:187], v[48:51]
	v_mfma_f32_16x16x32_bf16 v[40:43], v[152:155], v[184:187], v[40:43]
	v_mfma_f32_16x16x32_bf16 v[28:31], v[138:141], v[192:195], v[28:31]
	v_mfma_f32_16x16x32_bf16 v[24:27], v[152:155], v[192:195], v[24:27]
	v_mfma_f32_16x16x32_bf16 v[16:19], v[138:141], v[200:203], v[16:19]
	v_mfma_f32_16x16x32_bf16 v[8:11], v[152:155], v[200:203], v[8:11]
	v_mfma_f32_16x16x32_bf16 v[60:63], v[148:151], v[180:183], v[60:63]
	v_mfma_f32_16x16x32_bf16 v[56:59], v[156:159], v[180:183], v[56:59]
	v_mfma_f32_16x16x32_bf16 v[48:51], v[148:151], v[188:191], v[48:51]
	v_mfma_f32_16x16x32_bf16 v[40:43], v[156:159], v[188:191], v[40:43]
	v_mfma_f32_16x16x32_bf16 v[28:31], v[148:151], v[196:199], v[28:31]
	v_mfma_f32_16x16x32_bf16 v[24:27], v[156:159], v[196:199], v[24:27]
	v_mfma_f32_16x16x32_bf16 v[16:19], v[148:151], v[204:207], v[16:19]
	v_mfma_f32_16x16x32_bf16 v[8:11], v[156:159], v[204:207], v[8:11]
	s_setprio 0
	s_setprio 1
	v_mfma_f32_16x16x32_bf16 v[52:55], v[160:163], v[176:179], v[52:55]
	v_mfma_f32_16x16x32_bf16 v[44:47], v[168:171], v[176:179], v[44:47]
	v_mfma_f32_16x16x32_bf16 v[36:39], v[160:163], v[184:187], v[36:39]
	v_mfma_f32_16x16x32_bf16 v[32:35], v[168:171], v[184:187], v[32:35]
	v_mfma_f32_16x16x32_bf16 v[20:23], v[160:163], v[192:195], v[20:23]
	v_mfma_f32_16x16x32_bf16 v[12:15], v[168:171], v[192:195], v[12:15]
	v_mfma_f32_16x16x32_bf16 v[4:7], v[160:163], v[200:203], v[4:7]
	v_mfma_f32_16x16x32_bf16 v[0:3], v[168:171], v[200:203], v[0:3]
	v_mfma_f32_16x16x32_bf16 v[52:55], v[164:167], v[180:183], v[52:55]
	v_mfma_f32_16x16x32_bf16 v[44:47], v[172:175], v[180:183], v[44:47]
	v_mfma_f32_16x16x32_bf16 v[36:39], v[164:167], v[188:191], v[36:39]
	v_mfma_f32_16x16x32_bf16 v[32:35], v[172:175], v[188:191], v[32:35]
	v_mfma_f32_16x16x32_bf16 v[20:23], v[164:167], v[196:199], v[20:23]
	v_mfma_f32_16x16x32_bf16 v[12:15], v[172:175], v[196:199], v[12:15]
	v_mfma_f32_16x16x32_bf16 v[4:7], v[164:167], v[204:207], v[4:7]
	v_mfma_f32_16x16x32_bf16 v[0:3], v[172:175], v[204:207], v[0:3]
	s_setprio 0
	s_barrier
	s_mov_b32 m0, s29
	s_nop 0
	global_load_lds_dwordx4 v130, s[24:25]
	s_add_i32 s49, 0, 0x18000
	v_add_u32_e32 v132, s49, v144
	s_add_i32 s50, 0, 0x1c000
	s_add_u32 s24, s24, 0x4000
	s_addc_u32 s25, s25, 0
	s_mov_b32 m0, s30
	s_nop 0
	global_load_lds_dwordx4 v128, s[24:25]
	s_mov_b32 m0, s31
	s_nop 0
	global_load_lds_dwordx4 v130, s[24:25]
	ds_read_b128 v[138:141], v132
	ds_read_b128 v[148:151], v132 offset:1024
	ds_read_b128 v[152:155], v132 offset:2048
	ds_read_b128 v[156:159], v132 offset:3072
	v_add_u32_e32 v132, s50, v144
	ds_read_b128 v[160:163], v132
	ds_read_b128 v[164:167], v132 offset:1024
	ds_read_b128 v[168:171], v132 offset:2048
	ds_read_b128 v[172:175], v132 offset:3072
	ds_read_b128 v[176:179], v147 offset:32768
	ds_read_b128 v[180:183], v147 offset:33792
	ds_read_b128 v[184:187], v147 offset:34816
	ds_read_b128 v[188:191], v147 offset:35840
	ds_read_b128 v[192:195], v147 offset:36864
	ds_read_b128 v[196:199], v147 offset:37888
	ds_read_b128 v[200:203], v147 offset:38912
	ds_read_b128 v[204:207], v147 offset:39936
	s_waitcnt vmcnt(8)
	s_waitcnt lgkmcnt(0)
	s_barrier
	s_setprio 1
	s_waitcnt lgkmcnt(0)
	v_mfma_f32_16x16x32_bf16 v[124:127], v[138:141], v[176:179], v[124:127]
	v_mfma_f32_16x16x32_bf16 v[120:123], v[152:155], v[176:179], v[120:123]
	v_mfma_f32_16x16x32_bf16 v[116:119], v[138:141], v[184:187], v[116:119]
	v_mfma_f32_16x16x32_bf16 v[104:107], v[152:155], v[184:187], v[104:107]
	v_mfma_f32_16x16x32_bf16 v[92:95], v[138:141], v[192:195], v[92:95]
	v_mfma_f32_16x16x32_bf16 v[88:91], v[152:155], v[192:195], v[88:91]
	v_mfma_f32_16x16x32_bf16 v[84:87], v[138:141], v[200:203], v[84:87]
	v_mfma_f32_16x16x32_bf16 v[72:75], v[152:155], v[200:203], v[72:75]
	v_mfma_f32_16x16x32_bf16 v[124:127], v[148:151], v[180:183], v[124:127]
	v_mfma_f32_16x16x32_bf16 v[120:123], v[156:159], v[180:183], v[120:123]
	v_mfma_f32_16x16x32_bf16 v[116:119], v[148:151], v[188:191], v[116:119]
	v_mfma_f32_16x16x32_bf16 v[104:107], v[156:159], v[188:191], v[104:107]
	v_mfma_f32_16x16x32_bf16 v[92:95], v[148:151], v[196:199], v[92:95]
	v_mfma_f32_16x16x32_bf16 v[88:91], v[156:159], v[196:199], v[88:91]
	v_mfma_f32_16x16x32_bf16 v[84:87], v[148:151], v[204:207], v[84:87]
	v_mfma_f32_16x16x32_bf16 v[72:75], v[156:159], v[204:207], v[72:75]
	s_setprio 0
	s_setprio 1
	v_mfma_f32_16x16x32_bf16 v[112:115], v[160:163], v[176:179], v[112:115]
	v_mfma_f32_16x16x32_bf16 v[108:111], v[168:171], v[176:179], v[108:111]
	v_mfma_f32_16x16x32_bf16 v[100:103], v[160:163], v[184:187], v[100:103]
	v_mfma_f32_16x16x32_bf16 v[96:99], v[168:171], v[184:187], v[96:99]
	v_mfma_f32_16x16x32_bf16 v[80:83], v[160:163], v[192:195], v[80:83]
	v_mfma_f32_16x16x32_bf16 v[76:79], v[168:171], v[192:195], v[76:79]
	v_mfma_f32_16x16x32_bf16 v[68:71], v[160:163], v[200:203], v[68:71]
	v_mfma_f32_16x16x32_bf16 v[64:67], v[168:171], v[200:203], v[64:67]
	v_mfma_f32_16x16x32_bf16 v[112:115], v[164:167], v[180:183], v[112:115]
	v_mfma_f32_16x16x32_bf16 v[108:111], v[172:175], v[180:183], v[108:111]
	v_mfma_f32_16x16x32_bf16 v[100:103], v[164:167], v[188:191], v[100:103]
	v_mfma_f32_16x16x32_bf16 v[96:99], v[172:175], v[188:191], v[96:99]
	v_mfma_f32_16x16x32_bf16 v[80:83], v[164:167], v[196:199], v[80:83]
	v_mfma_f32_16x16x32_bf16 v[76:79], v[172:175], v[196:199], v[76:79]
	v_mfma_f32_16x16x32_bf16 v[68:71], v[164:167], v[204:207], v[68:71]
	v_mfma_f32_16x16x32_bf16 v[64:67], v[172:175], v[204:207], v[64:67]
	s_setprio 0
	s_barrier
	s_add_u32 s24, s22, 0x8000
	s_addc_u32 s25, s23, 0
	s_add_i32 s49, s49, s3
	s_mov_b32 m0, s49
	s_nop 0
	global_load_lds_dwordx4 v128, s[24:25]
	s_add_i32 m0, s49, 0x2000
	s_add_u32 s22, s22, 0xc000
	s_addc_u32 s23, s23, 0
	global_load_lds_dwordx4 v130, s[24:25]
	s_add_i32 s24, s50, s3
	s_mov_b32 m0, s24
	s_nop 0
	global_load_lds_dwordx4 v128, s[22:23]
	s_add_i32 m0, s24, 0x2000
	s_nop 0
	global_load_lds_dwordx4 v130, s[22:23]
	s_mov_b32 m0, s36
	s_nop 0
	global_load_lds_dwordx4 v128, s[20:21]
	s_mov_b32 m0, s37
	s_nop 0
	global_load_lds_dwordx4 v130, s[20:21]
	ds_read_b128 v[176:179], v147 offset:49152
	ds_read_b128 v[180:183], v147 offset:50176
	ds_read_b128 v[184:187], v147 offset:51200
	ds_read_b128 v[188:191], v147 offset:52224
	ds_read_b128 v[192:195], v147 offset:53248
	ds_read_b128 v[196:199], v147 offset:54272
	ds_read_b128 v[200:203], v147 offset:55296
	ds_read_b128 v[204:207], v147 offset:56320
	s_waitcnt vmcnt(8)
	s_waitcnt lgkmcnt(0)
	s_barrier
	s_setprio 1
	s_waitcnt lgkmcnt(0)
	v_mfma_f32_16x16x32_bf16 v[60:63], v[138:141], v[176:179], v[60:63]
	v_mfma_f32_16x16x32_bf16 v[56:59], v[152:155], v[176:179], v[56:59]
	v_mfma_f32_16x16x32_bf16 v[48:51], v[138:141], v[184:187], v[48:51]
	v_mfma_f32_16x16x32_bf16 v[40:43], v[152:155], v[184:187], v[40:43]
	v_mfma_f32_16x16x32_bf16 v[28:31], v[138:141], v[192:195], v[28:31]
	v_mfma_f32_16x16x32_bf16 v[24:27], v[152:155], v[192:195], v[24:27]
	v_mfma_f32_16x16x32_bf16 v[16:19], v[138:141], v[200:203], v[16:19]
	v_mfma_f32_16x16x32_bf16 v[8:11], v[152:155], v[200:203], v[8:11]
	v_mfma_f32_16x16x32_bf16 v[60:63], v[148:151], v[180:183], v[60:63]
	v_mfma_f32_16x16x32_bf16 v[56:59], v[156:159], v[180:183], v[56:59]
	v_mfma_f32_16x16x32_bf16 v[48:51], v[148:151], v[188:191], v[48:51]
	v_mfma_f32_16x16x32_bf16 v[40:43], v[156:159], v[188:191], v[40:43]
	v_mfma_f32_16x16x32_bf16 v[28:31], v[148:151], v[196:199], v[28:31]
	v_mfma_f32_16x16x32_bf16 v[24:27], v[156:159], v[196:199], v[24:27]
	v_mfma_f32_16x16x32_bf16 v[16:19], v[148:151], v[204:207], v[16:19]
	v_mfma_f32_16x16x32_bf16 v[8:11], v[156:159], v[204:207], v[8:11]
	s_setprio 0
	s_setprio 1
	v_mfma_f32_16x16x32_bf16 v[52:55], v[160:163], v[176:179], v[52:55]
	v_mfma_f32_16x16x32_bf16 v[44:47], v[168:171], v[176:179], v[44:47]
	v_mfma_f32_16x16x32_bf16 v[36:39], v[160:163], v[184:187], v[36:39]
	v_mfma_f32_16x16x32_bf16 v[32:35], v[168:171], v[184:187], v[32:35]
	v_mfma_f32_16x16x32_bf16 v[20:23], v[160:163], v[192:195], v[20:23]
	v_mfma_f32_16x16x32_bf16 v[12:15], v[168:171], v[192:195], v[12:15]
	v_mfma_f32_16x16x32_bf16 v[4:7], v[160:163], v[200:203], v[4:7]
	v_mfma_f32_16x16x32_bf16 v[0:3], v[168:171], v[200:203], v[0:3]
	v_mfma_f32_16x16x32_bf16 v[52:55], v[164:167], v[180:183], v[52:55]
	v_mfma_f32_16x16x32_bf16 v[44:47], v[172:175], v[180:183], v[44:47]
	v_mfma_f32_16x16x32_bf16 v[36:39], v[164:167], v[188:191], v[36:39]
	v_mfma_f32_16x16x32_bf16 v[32:35], v[172:175], v[188:191], v[32:35]
	v_mfma_f32_16x16x32_bf16 v[20:23], v[164:167], v[196:199], v[20:23]
	v_mfma_f32_16x16x32_bf16 v[12:15], v[172:175], v[196:199], v[12:15]
	v_mfma_f32_16x16x32_bf16 v[4:7], v[164:167], v[204:207], v[4:7]
	v_mfma_f32_16x16x32_bf16 v[0:3], v[172:175], v[204:207], v[0:3]
	s_setprio 0
	s_barrier
	s_add_i32 s48, s48, 2
	s_add_u32 s18, s18, 0x10000
	s_addc_u32 s19, s19, 0
	s_add_u32 s46, s46, 0x10000
	s_addc_u32 s47, s47, 0
	s_cmp_gt_u32 s48, 61
	s_cbranch_scc0 .LBB0_716
	s_and_b64 vcc, exec, s[6:7]
	s_cbranch_vccz .LBB0_719
	s_barrier
